# EpiRes epilogue rewrite: 16 residual loads hoisted, counted waits, atomics batched; EpiUp ssq loads hoisted
# speedup vs baseline: 1.0062x; 1.0062x over previous
.LBB0_710:
	s_add_u32 s24, s22, 0xfffc0080
	s_addc_u32 s25, s23, -1
	s_add_i32 vcc_lo, 0, 0x10000
	s_cmp_eq_u32 s92, 12
	s_cselect_b32 s27, s17, s25
	s_cselect_b32 s26, s70, s24
	v_add_u32_e32 v142, vcc_lo, v145
	s_cselect_b32 s25, s15, s83
	s_cselect_b32 s24, s80, s82
	s_add_i32 s10, 0, 0x14000
	ds_read_b128 v[138:141], v142
	ds_read_b128 v[148:151], v142 offset:1024
	ds_read_b128 v[152:155], v142 offset:2048
	ds_read_b128 v[156:159], v142 offset:3072
	v_add_u32_e32 v142, s10, v145
	ds_read_b128 v[160:163], v142
	ds_read_b128 v[164:167], v142 offset:1024
	ds_read_b128 v[168:171], v142 offset:2048
	ds_read_b128 v[172:175], v142 offset:3072
	v_lshl_add_u64 v[142:143], s[22:23], 0, v[134:135]
	s_add_i32 m0, s31, 0xc000
	ds_read_b128 v[176:179], v147
	ds_read_b128 v[180:183], v147 offset:1024
	ds_read_b128 v[184:187], v147 offset:2048
	ds_read_b128 v[188:191], v147 offset:3072
	ds_read_b128 v[192:195], v147 offset:4096
	ds_read_b128 v[196:199], v147 offset:5120
	ds_read_b128 v[200:203], v147 offset:6144
	ds_read_b128 v[204:207], v147 offset:7168
	global_load_lds_dwordx4 v[142:143], off
	v_lshl_add_u64 v[142:143], s[22:23], 0, v[136:137]
	s_add_i32 m0, s31, 0xe000
	s_nop 0
	global_load_lds_dwordx4 v[142:143], off
	s_waitcnt vmcnt(8)
	s_waitcnt lgkmcnt(0)
	s_barrier
	s_setprio 1
	s_waitcnt lgkmcnt(0)
	v_mfma_f32_16x16x32_bf16 v[124:127], v[138:141], v[176:179], v[124:127]
	v_mfma_f32_16x16x32_bf16 v[120:123], v[152:155], v[176:179], v[120:123]
	v_mfma_f32_16x16x32_bf16 v[108:111], v[138:141], v[184:187], v[108:111]
	v_mfma_f32_16x16x32_bf16 v[104:107], v[152:155], v[184:187], v[104:107]
	v_mfma_f32_16x16x32_bf16 v[92:95], v[138:141], v[192:195], v[92:95]
	v_mfma_f32_16x16x32_bf16 v[88:91], v[152:155], v[192:195], v[88:91]
	v_mfma_f32_16x16x32_bf16 v[76:79], v[138:141], v[200:203], v[76:79]
	v_mfma_f32_16x16x32_bf16 v[72:75], v[152:155], v[200:203], v[72:75]
	v_mfma_f32_16x16x32_bf16 v[124:127], v[148:151], v[180:183], v[124:127]
	v_mfma_f32_16x16x32_bf16 v[120:123], v[156:159], v[180:183], v[120:123]
	v_mfma_f32_16x16x32_bf16 v[108:111], v[148:151], v[188:191], v[108:111]
	v_mfma_f32_16x16x32_bf16 v[104:107], v[156:159], v[188:191], v[104:107]
	v_mfma_f32_16x16x32_bf16 v[92:95], v[148:151], v[196:199], v[92:95]
	v_mfma_f32_16x16x32_bf16 v[88:91], v[156:159], v[196:199], v[88:91]
	v_mfma_f32_16x16x32_bf16 v[76:79], v[148:151], v[204:207], v[76:79]
	v_mfma_f32_16x16x32_bf16 v[72:75], v[156:159], v[204:207], v[72:75]
	s_setprio 0
	s_setprio 1
	v_mfma_f32_16x16x32_bf16 v[116:119], v[160:163], v[176:179], v[116:119]
	v_mfma_f32_16x16x32_bf16 v[112:115], v[168:171], v[176:179], v[112:115]
	v_mfma_f32_16x16x32_bf16 v[100:103], v[160:163], v[184:187], v[100:103]
	v_mfma_f32_16x16x32_bf16 v[96:99], v[168:171], v[184:187], v[96:99]
	v_mfma_f32_16x16x32_bf16 v[84:87], v[160:163], v[192:195], v[84:87]
	v_mfma_f32_16x16x32_bf16 v[80:83], v[168:171], v[192:195], v[80:83]
	v_mfma_f32_16x16x32_bf16 v[68:71], v[160:163], v[200:203], v[68:71]
	v_mfma_f32_16x16x32_bf16 v[64:67], v[168:171], v[200:203], v[64:67]
	v_mfma_f32_16x16x32_bf16 v[116:119], v[164:167], v[180:183], v[116:119]
	v_mfma_f32_16x16x32_bf16 v[112:115], v[172:175], v[180:183], v[112:115]
	v_mfma_f32_16x16x32_bf16 v[100:103], v[164:167], v[188:191], v[100:103]
	v_mfma_f32_16x16x32_bf16 v[96:99], v[172:175], v[188:191], v[96:99]
	v_mfma_f32_16x16x32_bf16 v[84:87], v[164:167], v[196:199], v[84:87]
	v_mfma_f32_16x16x32_bf16 v[80:83], v[172:175], v[196:199], v[80:83]
	v_mfma_f32_16x16x32_bf16 v[68:71], v[164:167], v[204:207], v[68:71]
	v_mfma_f32_16x16x32_bf16 v[64:67], v[172:175], v[204:207], v[64:67]
	s_setprio 0
	s_barrier
	s_add_i32 s11, vcc_lo, s30
	v_lshl_add_u64 v[142:143], s[24:25], 0, v[208:209]
	s_mov_b32 m0, s11
	ds_read_b128 v[176:179], v147 offset:16384
	ds_read_b128 v[180:183], v147 offset:17408
	ds_read_b128 v[184:187], v147 offset:18432
	ds_read_b128 v[188:191], v147 offset:19456
	ds_read_b128 v[192:195], v147 offset:20480
	ds_read_b128 v[196:199], v147 offset:21504
	ds_read_b128 v[200:203], v147 offset:22528
	ds_read_b128 v[204:207], v147 offset:23552
	global_load_lds_dwordx4 v[142:143], off
	s_add_i32 m0, s11, 0x2000
	s_add_u32 vcc_lo, s24, 0x40000
	v_lshl_add_u64 v[222:223], s[24:25], 0, v[128:129]
	s_addc_u32 vcc_hi, s25, 0
	s_add_i32 s10, s10, s30
	global_load_lds_dwordx4 v[222:223], off
	v_lshl_add_u64 v[224:225], vcc, 0, v[208:209]
	s_mov_b32 m0, s10
	v_lshl_add_u64 v[236:237], s[26:27], 0, v[130:131]
	global_load_lds_dwordx4 v[224:225], off
	v_lshl_add_u64 v[224:225], vcc, 0, v[128:129]
	s_add_i32 m0, s10, 0x2000
	s_nop 0
	global_load_lds_dwordx4 v[224:225], off
	v_lshl_add_u64 v[224:225], s[26:27], 0, v[132:133]
	s_mov_b32 m0, s31
	s_nop 0
	global_load_lds_dwordx4 v[224:225], off
	s_mov_b32 m0, s34
	s_nop 0
	global_load_lds_dwordx4 v[236:237], off
	s_waitcnt vmcnt(8)
	s_waitcnt lgkmcnt(0)
	s_barrier
	s_setprio 1
	s_waitcnt lgkmcnt(0)
	v_mfma_f32_16x16x32_bf16 v[60:63], v[138:141], v[176:179], v[60:63]
	v_mfma_f32_16x16x32_bf16 v[56:59], v[152:155], v[176:179], v[56:59]
	v_mfma_f32_16x16x32_bf16 v[44:47], v[138:141], v[184:187], v[44:47]
	v_mfma_f32_16x16x32_bf16 v[40:43], v[152:155], v[184:187], v[40:43]
	v_mfma_f32_16x16x32_bf16 v[28:31], v[138:141], v[192:195], v[28:31]
	v_mfma_f32_16x16x32_bf16 v[24:27], v[152:155], v[192:195], v[24:27]
	v_mfma_f32_16x16x32_bf16 v[12:15], v[138:141], v[200:203], v[12:15]
	v_mfma_f32_16x16x32_bf16 v[8:11], v[152:155], v[200:203], v[8:11]
	v_mfma_f32_16x16x32_bf16 v[60:63], v[148:151], v[180:183], v[60:63]
	v_mfma_f32_16x16x32_bf16 v[56:59], v[156:159], v[180:183], v[56:59]
	v_mfma_f32_16x16x32_bf16 v[44:47], v[148:151], v[188:191], v[44:47]
	v_mfma_f32_16x16x32_bf16 v[40:43], v[156:159], v[188:191], v[40:43]
	v_mfma_f32_16x16x32_bf16 v[28:31], v[148:151], v[196:199], v[28:31]
	v_mfma_f32_16x16x32_bf16 v[24:27], v[156:159], v[196:199], v[24:27]
	v_mfma_f32_16x16x32_bf16 v[12:15], v[148:151], v[204:207], v[12:15]
	v_mfma_f32_16x16x32_bf16 v[8:11], v[156:159], v[204:207], v[8:11]
	s_setprio 0
	s_setprio 1
	v_mfma_f32_16x16x32_bf16 v[52:55], v[160:163], v[176:179], v[52:55]
	v_mfma_f32_16x16x32_bf16 v[48:51], v[168:171], v[176:179], v[48:51]
	v_mfma_f32_16x16x32_bf16 v[36:39], v[160:163], v[184:187], v[36:39]
	v_mfma_f32_16x16x32_bf16 v[32:35], v[168:171], v[184:187], v[32:35]
	v_mfma_f32_16x16x32_bf16 v[20:23], v[160:163], v[192:195], v[20:23]
	v_mfma_f32_16x16x32_bf16 v[16:19], v[168:171], v[192:195], v[16:19]
	v_mfma_f32_16x16x32_bf16 v[4:7], v[160:163], v[200:203], v[4:7]
	v_mfma_f32_16x16x32_bf16 v[0:3], v[168:171], v[200:203], v[0:3]
	v_mfma_f32_16x16x32_bf16 v[52:55], v[164:167], v[180:183], v[52:55]
	v_mfma_f32_16x16x32_bf16 v[48:51], v[172:175], v[180:183], v[48:51]
	v_mfma_f32_16x16x32_bf16 v[36:39], v[164:167], v[188:191], v[36:39]
	v_mfma_f32_16x16x32_bf16 v[32:35], v[172:175], v[188:191], v[32:35]
	v_mfma_f32_16x16x32_bf16 v[20:23], v[164:167], v[196:199], v[20:23]
	v_mfma_f32_16x16x32_bf16 v[16:19], v[172:175], v[196:199], v[16:19]
	v_mfma_f32_16x16x32_bf16 v[4:7], v[164:167], v[204:207], v[4:7]
	v_mfma_f32_16x16x32_bf16 v[0:3], v[172:175], v[204:207], v[0:3]
	s_setprio 0
	s_barrier
	s_add_i32 s10, 0, 0x18000
	s_add_i32 s11, 0, 0x1c000
	v_add_u32_e32 v156, s10, v145
	v_add_u32_e32 v172, s11, v145
	ds_read_b128 v[138:141], v156
	ds_read_b128 v[148:151], v156 offset:1024
	ds_read_b128 v[152:155], v156 offset:2048
	ds_read_b128 v[156:159], v156 offset:3072
	ds_read_b128 v[160:163], v172
	ds_read_b128 v[164:167], v172 offset:1024
	ds_read_b128 v[168:171], v172 offset:2048
	ds_read_b128 v[172:175], v172 offset:3072
	s_add_u32 s26, s26, 0x40000
	s_addc_u32 s27, s27, 0
	s_mov_b32 m0, s35
	v_lshl_add_u64 v[238:239], s[26:27], 0, v[132:133]
	ds_read_b128 v[176:179], v147 offset:32768
	ds_read_b128 v[180:183], v147 offset:33792
	ds_read_b128 v[184:187], v147 offset:34816
	ds_read_b128 v[188:191], v147 offset:35840
	ds_read_b128 v[192:195], v147 offset:36864
	ds_read_b128 v[196:199], v147 offset:37888
	ds_read_b128 v[200:203], v147 offset:38912
	ds_read_b128 v[204:207], v147 offset:39936
	global_load_lds_dwordx4 v[238:239], off
	v_lshl_add_u64 v[238:239], s[26:27], 0, v[130:131]
	s_mov_b32 m0, s36
	s_nop 0
	global_load_lds_dwordx4 v[238:239], off
	s_waitcnt vmcnt(8)
	s_waitcnt lgkmcnt(0)
	s_barrier
	s_setprio 1
	s_waitcnt lgkmcnt(0)
	v_mfma_f32_16x16x32_bf16 v[124:127], v[138:141], v[176:179], v[124:127]
	v_mfma_f32_16x16x32_bf16 v[120:123], v[152:155], v[176:179], v[120:123]
	v_mfma_f32_16x16x32_bf16 v[108:111], v[138:141], v[184:187], v[108:111]
	v_mfma_f32_16x16x32_bf16 v[104:107], v[152:155], v[184:187], v[104:107]
	v_mfma_f32_16x16x32_bf16 v[92:95], v[138:141], v[192:195], v[92:95]
	v_mfma_f32_16x16x32_bf16 v[88:91], v[152:155], v[192:195], v[88:91]
	v_mfma_f32_16x16x32_bf16 v[76:79], v[138:141], v[200:203], v[76:79]
	v_mfma_f32_16x16x32_bf16 v[72:75], v[152:155], v[200:203], v[72:75]
	v_mfma_f32_16x16x32_bf16 v[124:127], v[148:151], v[180:183], v[124:127]
	v_mfma_f32_16x16x32_bf16 v[120:123], v[156:159], v[180:183], v[120:123]
	v_mfma_f32_16x16x32_bf16 v[108:111], v[148:151], v[188:191], v[108:111]
	v_mfma_f32_16x16x32_bf16 v[104:107], v[156:159], v[188:191], v[104:107]
	v_mfma_f32_16x16x32_bf16 v[92:95], v[148:151], v[196:199], v[92:95]
	v_mfma_f32_16x16x32_bf16 v[88:91], v[156:159], v[196:199], v[88:91]
	v_mfma_f32_16x16x32_bf16 v[76:79], v[148:151], v[204:207], v[76:79]
	v_mfma_f32_16x16x32_bf16 v[72:75], v[156:159], v[204:207], v[72:75]
	s_setprio 0
	s_setprio 1
	v_mfma_f32_16x16x32_bf16 v[116:119], v[160:163], v[176:179], v[116:119]
	v_mfma_f32_16x16x32_bf16 v[112:115], v[168:171], v[176:179], v[112:115]
	v_mfma_f32_16x16x32_bf16 v[100:103], v[160:163], v[184:187], v[100:103]
	v_mfma_f32_16x16x32_bf16 v[96:99], v[168:171], v[184:187], v[96:99]
	v_mfma_f32_16x16x32_bf16 v[84:87], v[160:163], v[192:195], v[84:87]
	v_mfma_f32_16x16x32_bf16 v[80:83], v[168:171], v[192:195], v[80:83]
	v_mfma_f32_16x16x32_bf16 v[68:71], v[160:163], v[200:203], v[68:71]
	v_mfma_f32_16x16x32_bf16 v[64:67], v[168:171], v[200:203], v[64:67]
	v_mfma_f32_16x16x32_bf16 v[116:119], v[164:167], v[180:183], v[116:119]
	v_mfma_f32_16x16x32_bf16 v[112:115], v[172:175], v[180:183], v[112:115]
	v_mfma_f32_16x16x32_bf16 v[100:103], v[164:167], v[188:191], v[100:103]
	v_mfma_f32_16x16x32_bf16 v[96:99], v[172:175], v[188:191], v[96:99]
	v_mfma_f32_16x16x32_bf16 v[84:87], v[164:167], v[196:199], v[84:87]
	v_mfma_f32_16x16x32_bf16 v[80:83], v[172:175], v[196:199], v[80:83]
	v_mfma_f32_16x16x32_bf16 v[68:71], v[164:167], v[204:207], v[68:71]
	v_mfma_f32_16x16x32_bf16 v[64:67], v[172:175], v[204:207], v[64:67]
	s_setprio 0
	s_barrier
	s_add_i32 s10, s10, s30
	v_lshl_add_u64 v[142:143], v[142:143], 0, s[94:95]
	s_mov_b32 m0, s10
	ds_read_b128 v[176:179], v147 offset:49152
	ds_read_b128 v[180:183], v147 offset:50176
	ds_read_b128 v[184:187], v147 offset:51200
	ds_read_b128 v[188:191], v147 offset:52224
	ds_read_b128 v[192:195], v147 offset:53248
	ds_read_b128 v[196:199], v147 offset:54272
	ds_read_b128 v[200:203], v147 offset:55296
	ds_read_b128 v[204:207], v147 offset:56320
	global_load_lds_dwordx4 v[142:143], off
	s_add_i32 m0, s10, 0x2000
	s_add_u32 s24, s24, 0x40080
	v_lshl_add_u64 v[142:143], v[222:223], 0, s[94:95]
	s_addc_u32 s25, s25, 0
	s_add_i32 s10, s11, s30
	global_load_lds_dwordx4 v[142:143], off
	v_lshl_add_u64 v[142:143], s[24:25], 0, v[208:209]
	s_mov_b32 m0, s10
	s_nop 0
	global_load_lds_dwordx4 v[142:143], off
	v_lshl_add_u64 v[142:143], s[24:25], 0, v[128:129]
	s_add_i32 m0, s10, 0x2000
	s_nop 0
	global_load_lds_dwordx4 v[142:143], off
	v_lshl_add_u64 v[142:143], v[224:225], 0, s[94:95]
	s_mov_b32 m0, s37
	s_nop 0
	global_load_lds_dwordx4 v[142:143], off
	v_lshl_add_u64 v[142:143], v[236:237], 0, s[94:95]
	s_mov_b32 m0, s40
	s_nop 0
	global_load_lds_dwordx4 v[142:143], off
	s_waitcnt vmcnt(8)
	s_waitcnt lgkmcnt(0)
	s_barrier
	s_setprio 1
	s_waitcnt lgkmcnt(0)
	v_mfma_f32_16x16x32_bf16 v[60:63], v[138:141], v[176:179], v[60:63]
	v_mfma_f32_16x16x32_bf16 v[56:59], v[152:155], v[176:179], v[56:59]
	v_mfma_f32_16x16x32_bf16 v[44:47], v[138:141], v[184:187], v[44:47]
	v_mfma_f32_16x16x32_bf16 v[40:43], v[152:155], v[184:187], v[40:43]
	v_mfma_f32_16x16x32_bf16 v[28:31], v[138:141], v[192:195], v[28:31]
	v_mfma_f32_16x16x32_bf16 v[24:27], v[152:155], v[192:195], v[24:27]
	v_mfma_f32_16x16x32_bf16 v[12:15], v[138:141], v[200:203], v[12:15]
	v_mfma_f32_16x16x32_bf16 v[8:11], v[152:155], v[200:203], v[8:11]
	v_mfma_f32_16x16x32_bf16 v[60:63], v[148:151], v[180:183], v[60:63]
	v_mfma_f32_16x16x32_bf16 v[56:59], v[156:159], v[180:183], v[56:59]
	v_mfma_f32_16x16x32_bf16 v[44:47], v[148:151], v[188:191], v[44:47]
	v_mfma_f32_16x16x32_bf16 v[40:43], v[156:159], v[188:191], v[40:43]
	v_mfma_f32_16x16x32_bf16 v[28:31], v[148:151], v[196:199], v[28:31]
	v_mfma_f32_16x16x32_bf16 v[24:27], v[156:159], v[196:199], v[24:27]
	v_mfma_f32_16x16x32_bf16 v[12:15], v[148:151], v[204:207], v[12:15]
	v_mfma_f32_16x16x32_bf16 v[8:11], v[156:159], v[204:207], v[8:11]
	s_setprio 0
	s_setprio 1
	v_mfma_f32_16x16x32_bf16 v[52:55], v[160:163], v[176:179], v[52:55]
	v_mfma_f32_16x16x32_bf16 v[48:51], v[168:171], v[176:179], v[48:51]
	v_mfma_f32_16x16x32_bf16 v[36:39], v[160:163], v[184:187], v[36:39]
	v_mfma_f32_16x16x32_bf16 v[32:35], v[168:171], v[184:187], v[32:35]
	v_mfma_f32_16x16x32_bf16 v[20:23], v[160:163], v[192:195], v[20:23]
	v_mfma_f32_16x16x32_bf16 v[16:19], v[168:171], v[192:195], v[16:19]
	v_mfma_f32_16x16x32_bf16 v[4:7], v[160:163], v[200:203], v[4:7]
	v_mfma_f32_16x16x32_bf16 v[0:3], v[168:171], v[200:203], v[0:3]
	v_mfma_f32_16x16x32_bf16 v[52:55], v[164:167], v[180:183], v[52:55]
	v_mfma_f32_16x16x32_bf16 v[48:51], v[172:175], v[180:183], v[48:51]
	v_mfma_f32_16x16x32_bf16 v[36:39], v[164:167], v[188:191], v[36:39]
	v_mfma_f32_16x16x32_bf16 v[32:35], v[172:175], v[188:191], v[32:35]
	v_mfma_f32_16x16x32_bf16 v[20:23], v[164:167], v[196:199], v[20:23]
	v_mfma_f32_16x16x32_bf16 v[16:19], v[172:175], v[196:199], v[16:19]
	v_mfma_f32_16x16x32_bf16 v[4:7], v[164:167], v[204:207], v[4:7]
	v_mfma_f32_16x16x32_bf16 v[0:3], v[172:175], v[204:207], v[0:3]
	s_setprio 0
	s_barrier
	s_add_i32 s92, s92, 2
	s_add_u32 s22, s22, 0x100
	s_addc_u32 s23, s23, 0
	s_add_u32 s82, s82, 0x100
	s_addc_u32 s83, s83, 0
	s_cmp_gt_u32 s92, 13
	s_cbranch_scc0 .LBB0_710
	v_lshl_add_u32 v140, s43, 8, v144
	v_lshl_or_b32 v138, s42, 8, v146
	v_lshlrev_b32_e32 v139, 2, v140
	v_lshlrev_b32_e32 v140, 11, v140
	v_lshl_add_u32 v138, v138, 1, v140
	s_mov_b64 s[100:101], s[46:47]
	global_load_dwordx4 v[148:151], v138, s[100:101]
	global_load_dwordx4 v[152:155], v138, s[100:101] offset:256
	s_add_u32 s100, s100, 0x8000
	s_addc_u32 s101, s101, 0
	global_load_dwordx4 v[156:159], v138, s[100:101]
	global_load_dwordx4 v[160:163], v138, s[100:101] offset:256
	s_add_u32 s100, s100, 0x8000
	s_addc_u32 s101, s101, 0
	global_load_dwordx4 v[164:167], v138, s[100:101]
	global_load_dwordx4 v[168:171], v138, s[100:101] offset:256
	s_add_u32 s100, s100, 0x8000
	s_addc_u32 s101, s101, 0
	global_load_dwordx4 v[172:175], v138, s[100:101]
	global_load_dwordx4 v[176:179], v138, s[100:101] offset:256
	s_add_u32 s100, s100, 0x28000
	s_addc_u32 s101, s101, 0
	global_load_dwordx4 v[180:183], v138, s[100:101]
	global_load_dwordx4 v[184:187], v138, s[100:101] offset:256
	s_add_u32 s100, s100, 0x8000
	s_addc_u32 s101, s101, 0
	global_load_dwordx4 v[188:191], v138, s[100:101]
	global_load_dwordx4 v[192:195], v138, s[100:101] offset:256
	s_add_u32 s100, s100, 0x8000
	s_addc_u32 s101, s101, 0
	global_load_dwordx4 v[196:199], v138, s[100:101]
	global_load_dwordx4 v[200:203], v138, s[100:101] offset:256
	s_add_u32 s100, s100, 0x8000
	s_addc_u32 s101, s101, 0
	global_load_dwordx4 v[204:207], v138, s[100:101]
	global_load_dwordx4 v[236:239], v138, s[100:101] offset:256
	s_and_b64 vcc, exec, s[12:13]
	s_cbranch_vccz .LBB0_713
	s_barrier
.LBB0_713:
	v_xor_b32_e32 v140, 16, v230
	v_xor_b32_e32 v141, 32, v230
	v_lshlrev_b32_e32 v140, 2, v140
	v_lshlrev_b32_e32 v141, 2, v141
	s_mov_b64 s[100:101], s[46:47]
	s_waitcnt vmcnt(14)
	v_lshlrev_b32_e32 v142, 16, v148
	v_and_b32_e32 v143, 0xffff0000, v148
	v_pk_add_f32 v[124:125], v[124:125], v[142:143]
	v_pk_mul_f32 v[222:223], v[124:125], v[124:125]
	v_cvt_pk_bf16_f32 v148, v124, v125
	v_lshlrev_b32_e32 v142, 16, v149
	v_and_b32_e32 v143, 0xffff0000, v149
	v_pk_add_f32 v[126:127], v[126:127], v[142:143]
	v_pk_fma_f32 v[222:223], v[126:127], v[126:127], v[222:223]
	v_cvt_pk_bf16_f32 v149, v126, v127
	v_lshlrev_b32_e32 v142, 16, v150
	v_and_b32_e32 v143, 0xffff0000, v150
	v_pk_add_f32 v[120:121], v[120:121], v[142:143]
	v_pk_fma_f32 v[222:223], v[120:121], v[120:121], v[222:223]
	v_cvt_pk_bf16_f32 v150, v120, v121
	v_lshlrev_b32_e32 v142, 16, v151
	v_and_b32_e32 v143, 0xffff0000, v151
	v_pk_add_f32 v[122:123], v[122:123], v[142:143]
	v_pk_fma_f32 v[222:223], v[122:123], v[122:123], v[222:223]
	v_cvt_pk_bf16_f32 v151, v122, v123
	global_store_dwordx4 v138, v[148:151], s[100:101]
	v_lshlrev_b32_e32 v142, 16, v152
	v_and_b32_e32 v143, 0xffff0000, v152
	v_pk_add_f32 v[116:117], v[116:117], v[142:143]
	v_pk_fma_f32 v[222:223], v[116:117], v[116:117], v[222:223]
	v_cvt_pk_bf16_f32 v152, v116, v117
	v_lshlrev_b32_e32 v142, 16, v153
	v_and_b32_e32 v143, 0xffff0000, v153
	v_pk_add_f32 v[118:119], v[118:119], v[142:143]
	v_pk_fma_f32 v[222:223], v[118:119], v[118:119], v[222:223]
	v_cvt_pk_bf16_f32 v153, v118, v119
	v_lshlrev_b32_e32 v142, 16, v154
	v_and_b32_e32 v143, 0xffff0000, v154
	v_pk_add_f32 v[112:113], v[112:113], v[142:143]
	v_pk_fma_f32 v[222:223], v[112:113], v[112:113], v[222:223]
	v_cvt_pk_bf16_f32 v154, v112, v113
	v_lshlrev_b32_e32 v142, 16, v155
	v_and_b32_e32 v143, 0xffff0000, v155
	v_pk_add_f32 v[114:115], v[114:115], v[142:143]
	v_pk_fma_f32 v[222:223], v[114:115], v[114:115], v[222:223]
	v_cvt_pk_bf16_f32 v155, v114, v115
	global_store_dwordx4 v138, v[152:155], s[100:101] offset:256
	v_add_f32_e32 v124, v222, v223
	s_add_u32 s100, s100, 0x8000
	s_addc_u32 s101, s101, 0
	s_waitcnt vmcnt(14)
	v_lshlrev_b32_e32 v142, 16, v156
	v_and_b32_e32 v143, 0xffff0000, v156
	v_pk_add_f32 v[108:109], v[108:109], v[142:143]
	v_pk_mul_f32 v[222:223], v[108:109], v[108:109]
	v_cvt_pk_bf16_f32 v156, v108, v109
	v_lshlrev_b32_e32 v142, 16, v157
	v_and_b32_e32 v143, 0xffff0000, v157
	v_pk_add_f32 v[110:111], v[110:111], v[142:143]
	v_pk_fma_f32 v[222:223], v[110:111], v[110:111], v[222:223]
	v_cvt_pk_bf16_f32 v157, v110, v111
	v_lshlrev_b32_e32 v142, 16, v158
	v_and_b32_e32 v143, 0xffff0000, v158
	v_pk_add_f32 v[104:105], v[104:105], v[142:143]
	v_pk_fma_f32 v[222:223], v[104:105], v[104:105], v[222:223]
	v_cvt_pk_bf16_f32 v158, v104, v105
	v_lshlrev_b32_e32 v142, 16, v159
	v_and_b32_e32 v143, 0xffff0000, v159
	v_pk_add_f32 v[106:107], v[106:107], v[142:143]
	v_pk_fma_f32 v[222:223], v[106:107], v[106:107], v[222:223]
	v_cvt_pk_bf16_f32 v159, v106, v107
	global_store_dwordx4 v138, v[156:159], s[100:101]
	v_lshlrev_b32_e32 v142, 16, v160
	v_and_b32_e32 v143, 0xffff0000, v160
	v_pk_add_f32 v[100:101], v[100:101], v[142:143]
	v_pk_fma_f32 v[222:223], v[100:101], v[100:101], v[222:223]
	v_cvt_pk_bf16_f32 v160, v100, v101
	v_lshlrev_b32_e32 v142, 16, v161
	v_and_b32_e32 v143, 0xffff0000, v161
	v_pk_add_f32 v[102:103], v[102:103], v[142:143]
	v_pk_fma_f32 v[222:223], v[102:103], v[102:103], v[222:223]
	v_cvt_pk_bf16_f32 v161, v102, v103
	v_lshlrev_b32_e32 v142, 16, v162
	v_and_b32_e32 v143, 0xffff0000, v162
	v_pk_add_f32 v[96:97], v[96:97], v[142:143]
	v_pk_fma_f32 v[222:223], v[96:97], v[96:97], v[222:223]
	v_cvt_pk_bf16_f32 v162, v96, v97
	v_lshlrev_b32_e32 v142, 16, v163
	v_and_b32_e32 v143, 0xffff0000, v163
	v_pk_add_f32 v[98:99], v[98:99], v[142:143]
	v_pk_fma_f32 v[222:223], v[98:99], v[98:99], v[222:223]
	v_cvt_pk_bf16_f32 v163, v98, v99
	global_store_dwordx4 v138, v[160:163], s[100:101] offset:256
	v_add_f32_e32 v108, v222, v223
	s_add_u32 s100, s100, 0x8000
	s_addc_u32 s101, s101, 0
	s_waitcnt vmcnt(14)
	v_lshlrev_b32_e32 v142, 16, v164
	v_and_b32_e32 v143, 0xffff0000, v164
	v_pk_add_f32 v[92:93], v[92:93], v[142:143]
	v_pk_mul_f32 v[222:223], v[92:93], v[92:93]
	v_cvt_pk_bf16_f32 v164, v92, v93
	v_lshlrev_b32_e32 v142, 16, v165
	v_and_b32_e32 v143, 0xffff0000, v165
	v_pk_add_f32 v[94:95], v[94:95], v[142:143]
	v_pk_fma_f32 v[222:223], v[94:95], v[94:95], v[222:223]
	v_cvt_pk_bf16_f32 v165, v94, v95
	v_lshlrev_b32_e32 v142, 16, v166
	v_and_b32_e32 v143, 0xffff0000, v166
	v_pk_add_f32 v[88:89], v[88:89], v[142:143]
	v_pk_fma_f32 v[222:223], v[88:89], v[88:89], v[222:223]
	v_cvt_pk_bf16_f32 v166, v88, v89
	v_lshlrev_b32_e32 v142, 16, v167
	v_and_b32_e32 v143, 0xffff0000, v167
	v_pk_add_f32 v[90:91], v[90:91], v[142:143]
	v_pk_fma_f32 v[222:223], v[90:91], v[90:91], v[222:223]
	v_cvt_pk_bf16_f32 v167, v90, v91
	global_store_dwordx4 v138, v[164:167], s[100:101]
	v_lshlrev_b32_e32 v142, 16, v168
	v_and_b32_e32 v143, 0xffff0000, v168
	v_pk_add_f32 v[84:85], v[84:85], v[142:143]
	v_pk_fma_f32 v[222:223], v[84:85], v[84:85], v[222:223]
	v_cvt_pk_bf16_f32 v168, v84, v85
	v_lshlrev_b32_e32 v142, 16, v169
	v_and_b32_e32 v143, 0xffff0000, v169
	v_pk_add_f32 v[86:87], v[86:87], v[142:143]
	v_pk_fma_f32 v[222:223], v[86:87], v[86:87], v[222:223]
	v_cvt_pk_bf16_f32 v169, v86, v87
	v_lshlrev_b32_e32 v142, 16, v170
	v_and_b32_e32 v143, 0xffff0000, v170
	v_pk_add_f32 v[80:81], v[80:81], v[142:143]
	v_pk_fma_f32 v[222:223], v[80:81], v[80:81], v[222:223]
	v_cvt_pk_bf16_f32 v170, v80, v81
	v_lshlrev_b32_e32 v142, 16, v171
	v_and_b32_e32 v143, 0xffff0000, v171
	v_pk_add_f32 v[82:83], v[82:83], v[142:143]
	v_pk_fma_f32 v[222:223], v[82:83], v[82:83], v[222:223]
	v_cvt_pk_bf16_f32 v171, v82, v83
	global_store_dwordx4 v138, v[168:171], s[100:101] offset:256
	v_add_f32_e32 v92, v222, v223
	s_add_u32 s100, s100, 0x8000
	s_addc_u32 s101, s101, 0
	s_waitcnt vmcnt(14)
	v_lshlrev_b32_e32 v142, 16, v172
	v_and_b32_e32 v143, 0xffff0000, v172
	v_pk_add_f32 v[76:77], v[76:77], v[142:143]
	v_pk_mul_f32 v[222:223], v[76:77], v[76:77]
	v_cvt_pk_bf16_f32 v172, v76, v77
	v_lshlrev_b32_e32 v142, 16, v173
	v_and_b32_e32 v143, 0xffff0000, v173
	v_pk_add_f32 v[78:79], v[78:79], v[142:143]
	v_pk_fma_f32 v[222:223], v[78:79], v[78:79], v[222:223]
	v_cvt_pk_bf16_f32 v173, v78, v79
	v_lshlrev_b32_e32 v142, 16, v174
	v_and_b32_e32 v143, 0xffff0000, v174
	v_pk_add_f32 v[72:73], v[72:73], v[142:143]
	v_pk_fma_f32 v[222:223], v[72:73], v[72:73], v[222:223]
	v_cvt_pk_bf16_f32 v174, v72, v73
	v_lshlrev_b32_e32 v142, 16, v175
	v_and_b32_e32 v143, 0xffff0000, v175
	v_pk_add_f32 v[74:75], v[74:75], v[142:143]
	v_pk_fma_f32 v[222:223], v[74:75], v[74:75], v[222:223]
	v_cvt_pk_bf16_f32 v175, v74, v75
	global_store_dwordx4 v138, v[172:175], s[100:101]
	v_lshlrev_b32_e32 v142, 16, v176
	v_and_b32_e32 v143, 0xffff0000, v176
	v_pk_add_f32 v[68:69], v[68:69], v[142:143]
	v_pk_fma_f32 v[222:223], v[68:69], v[68:69], v[222:223]
	v_cvt_pk_bf16_f32 v176, v68, v69
	v_lshlrev_b32_e32 v142, 16, v177
	v_and_b32_e32 v143, 0xffff0000, v177
	v_pk_add_f32 v[70:71], v[70:71], v[142:143]
	v_pk_fma_f32 v[222:223], v[70:71], v[70:71], v[222:223]
	v_cvt_pk_bf16_f32 v177, v70, v71
	v_lshlrev_b32_e32 v142, 16, v178
	v_and_b32_e32 v143, 0xffff0000, v178
	v_pk_add_f32 v[64:65], v[64:65], v[142:143]
	v_pk_fma_f32 v[222:223], v[64:65], v[64:65], v[222:223]
	v_cvt_pk_bf16_f32 v178, v64, v65
	v_lshlrev_b32_e32 v142, 16, v179
	v_and_b32_e32 v143, 0xffff0000, v179
	v_pk_add_f32 v[66:67], v[66:67], v[142:143]
	v_pk_fma_f32 v[222:223], v[66:67], v[66:67], v[222:223]
	v_cvt_pk_bf16_f32 v179, v66, v67
	global_store_dwordx4 v138, v[176:179], s[100:101] offset:256
	v_add_f32_e32 v76, v222, v223
	s_add_u32 s100, s100, 0x28000
	s_addc_u32 s101, s101, 0
	s_waitcnt vmcnt(14)
	v_lshlrev_b32_e32 v142, 16, v180
	v_and_b32_e32 v143, 0xffff0000, v180
	v_pk_add_f32 v[60:61], v[60:61], v[142:143]
	v_pk_mul_f32 v[222:223], v[60:61], v[60:61]
	v_cvt_pk_bf16_f32 v180, v60, v61
	v_lshlrev_b32_e32 v142, 16, v181
	v_and_b32_e32 v143, 0xffff0000, v181
	v_pk_add_f32 v[62:63], v[62:63], v[142:143]
	v_pk_fma_f32 v[222:223], v[62:63], v[62:63], v[222:223]
	v_cvt_pk_bf16_f32 v181, v62, v63
	v_lshlrev_b32_e32 v142, 16, v182
	v_and_b32_e32 v143, 0xffff0000, v182
	v_pk_add_f32 v[56:57], v[56:57], v[142:143]
	v_pk_fma_f32 v[222:223], v[56:57], v[56:57], v[222:223]
	v_cvt_pk_bf16_f32 v182, v56, v57
	v_lshlrev_b32_e32 v142, 16, v183
	v_and_b32_e32 v143, 0xffff0000, v183
	v_pk_add_f32 v[58:59], v[58:59], v[142:143]
	v_pk_fma_f32 v[222:223], v[58:59], v[58:59], v[222:223]
	v_cvt_pk_bf16_f32 v183, v58, v59
	global_store_dwordx4 v138, v[180:183], s[100:101]
	v_lshlrev_b32_e32 v142, 16, v184
	v_and_b32_e32 v143, 0xffff0000, v184
	v_pk_add_f32 v[52:53], v[52:53], v[142:143]
	v_pk_fma_f32 v[222:223], v[52:53], v[52:53], v[222:223]
	v_cvt_pk_bf16_f32 v184, v52, v53
	v_lshlrev_b32_e32 v142, 16, v185
	v_and_b32_e32 v143, 0xffff0000, v185
	v_pk_add_f32 v[54:55], v[54:55], v[142:143]
	v_pk_fma_f32 v[222:223], v[54:55], v[54:55], v[222:223]
	v_cvt_pk_bf16_f32 v185, v54, v55
	v_lshlrev_b32_e32 v142, 16, v186
	v_and_b32_e32 v143, 0xffff0000, v186
	v_pk_add_f32 v[48:49], v[48:49], v[142:143]
	v_pk_fma_f32 v[222:223], v[48:49], v[48:49], v[222:223]
	v_cvt_pk_bf16_f32 v186, v48, v49
	v_lshlrev_b32_e32 v142, 16, v187
	v_and_b32_e32 v143, 0xffff0000, v187
	v_pk_add_f32 v[50:51], v[50:51], v[142:143]
	v_pk_fma_f32 v[222:223], v[50:51], v[50:51], v[222:223]
	v_cvt_pk_bf16_f32 v187, v50, v51
	global_store_dwordx4 v138, v[184:187], s[100:101] offset:256
	v_add_f32_e32 v60, v222, v223
	s_add_u32 s100, s100, 0x8000
	s_addc_u32 s101, s101, 0
	s_waitcnt vmcnt(14)
	v_lshlrev_b32_e32 v142, 16, v188
	v_and_b32_e32 v143, 0xffff0000, v188
	v_pk_add_f32 v[44:45], v[44:45], v[142:143]
	v_pk_mul_f32 v[222:223], v[44:45], v[44:45]
	v_cvt_pk_bf16_f32 v188, v44, v45
	v_lshlrev_b32_e32 v142, 16, v189
	v_and_b32_e32 v143, 0xffff0000, v189
	v_pk_add_f32 v[46:47], v[46:47], v[142:143]
	v_pk_fma_f32 v[222:223], v[46:47], v[46:47], v[222:223]
	v_cvt_pk_bf16_f32 v189, v46, v47
	v_lshlrev_b32_e32 v142, 16, v190
	v_and_b32_e32 v143, 0xffff0000, v190
	v_pk_add_f32 v[40:41], v[40:41], v[142:143]
	v_pk_fma_f32 v[222:223], v[40:41], v[40:41], v[222:223]
	v_cvt_pk_bf16_f32 v190, v40, v41
	v_lshlrev_b32_e32 v142, 16, v191
	v_and_b32_e32 v143, 0xffff0000, v191
	v_pk_add_f32 v[42:43], v[42:43], v[142:143]
	v_pk_fma_f32 v[222:223], v[42:43], v[42:43], v[222:223]
	v_cvt_pk_bf16_f32 v191, v42, v43
	global_store_dwordx4 v138, v[188:191], s[100:101]
	v_lshlrev_b32_e32 v142, 16, v192
	v_and_b32_e32 v143, 0xffff0000, v192
	v_pk_add_f32 v[36:37], v[36:37], v[142:143]
	v_pk_fma_f32 v[222:223], v[36:37], v[36:37], v[222:223]
	v_cvt_pk_bf16_f32 v192, v36, v37
	v_lshlrev_b32_e32 v142, 16, v193
	v_and_b32_e32 v143, 0xffff0000, v193
	v_pk_add_f32 v[38:39], v[38:39], v[142:143]
	v_pk_fma_f32 v[222:223], v[38:39], v[38:39], v[222:223]
	v_cvt_pk_bf16_f32 v193, v38, v39
	v_lshlrev_b32_e32 v142, 16, v194
	v_and_b32_e32 v143, 0xffff0000, v194
	v_pk_add_f32 v[32:33], v[32:33], v[142:143]
	v_pk_fma_f32 v[222:223], v[32:33], v[32:33], v[222:223]
	v_cvt_pk_bf16_f32 v194, v32, v33
	v_lshlrev_b32_e32 v142, 16, v195
	v_and_b32_e32 v143, 0xffff0000, v195
	v_pk_add_f32 v[34:35], v[34:35], v[142:143]
	v_pk_fma_f32 v[222:223], v[34:35], v[34:35], v[222:223]
	v_cvt_pk_bf16_f32 v195, v34, v35
	global_store_dwordx4 v138, v[192:195], s[100:101] offset:256
	v_add_f32_e32 v44, v222, v223
	s_add_u32 s100, s100, 0x8000
	s_addc_u32 s101, s101, 0
	s_waitcnt vmcnt(14)
	v_lshlrev_b32_e32 v142, 16, v196
	v_and_b32_e32 v143, 0xffff0000, v196
	v_pk_add_f32 v[28:29], v[28:29], v[142:143]
	v_pk_mul_f32 v[222:223], v[28:29], v[28:29]
	v_cvt_pk_bf16_f32 v196, v28, v29
	v_lshlrev_b32_e32 v142, 16, v197
	v_and_b32_e32 v143, 0xffff0000, v197
	v_pk_add_f32 v[30:31], v[30:31], v[142:143]
	v_pk_fma_f32 v[222:223], v[30:31], v[30:31], v[222:223]
	v_cvt_pk_bf16_f32 v197, v30, v31
	v_lshlrev_b32_e32 v142, 16, v198
	v_and_b32_e32 v143, 0xffff0000, v198
	v_pk_add_f32 v[24:25], v[24:25], v[142:143]
	v_pk_fma_f32 v[222:223], v[24:25], v[24:25], v[222:223]
	v_cvt_pk_bf16_f32 v198, v24, v25
	v_lshlrev_b32_e32 v142, 16, v199
	v_and_b32_e32 v143, 0xffff0000, v199
	v_pk_add_f32 v[26:27], v[26:27], v[142:143]
	v_pk_fma_f32 v[222:223], v[26:27], v[26:27], v[222:223]
	v_cvt_pk_bf16_f32 v199, v26, v27
	global_store_dwordx4 v138, v[196:199], s[100:101]
	v_lshlrev_b32_e32 v142, 16, v200
	v_and_b32_e32 v143, 0xffff0000, v200
	v_pk_add_f32 v[20:21], v[20:21], v[142:143]
	v_pk_fma_f32 v[222:223], v[20:21], v[20:21], v[222:223]
	v_cvt_pk_bf16_f32 v200, v20, v21
	v_lshlrev_b32_e32 v142, 16, v201
	v_and_b32_e32 v143, 0xffff0000, v201
	v_pk_add_f32 v[22:23], v[22:23], v[142:143]
	v_pk_fma_f32 v[222:223], v[22:23], v[22:23], v[222:223]
	v_cvt_pk_bf16_f32 v201, v22, v23
	v_lshlrev_b32_e32 v142, 16, v202
	v_and_b32_e32 v143, 0xffff0000, v202
	v_pk_add_f32 v[16:17], v[16:17], v[142:143]
	v_pk_fma_f32 v[222:223], v[16:17], v[16:17], v[222:223]
	v_cvt_pk_bf16_f32 v202, v16, v17
	v_lshlrev_b32_e32 v142, 16, v203
	v_and_b32_e32 v143, 0xffff0000, v203
	v_pk_add_f32 v[18:19], v[18:19], v[142:143]
	v_pk_fma_f32 v[222:223], v[18:19], v[18:19], v[222:223]
	v_cvt_pk_bf16_f32 v203, v18, v19
	global_store_dwordx4 v138, v[200:203], s[100:101] offset:256
	v_add_f32_e32 v28, v222, v223
	s_add_u32 s100, s100, 0x8000
	s_addc_u32 s101, s101, 0
	s_waitcnt vmcnt(14)
	v_lshlrev_b32_e32 v142, 16, v204
	v_and_b32_e32 v143, 0xffff0000, v204
	v_pk_add_f32 v[12:13], v[12:13], v[142:143]
	v_pk_mul_f32 v[222:223], v[12:13], v[12:13]
	v_cvt_pk_bf16_f32 v204, v12, v13
	v_lshlrev_b32_e32 v142, 16, v205
	v_and_b32_e32 v143, 0xffff0000, v205
	v_pk_add_f32 v[14:15], v[14:15], v[142:143]
	v_pk_fma_f32 v[222:223], v[14:15], v[14:15], v[222:223]
	v_cvt_pk_bf16_f32 v205, v14, v15
	v_lshlrev_b32_e32 v142, 16, v206
	v_and_b32_e32 v143, 0xffff0000, v206
	v_pk_add_f32 v[8:9], v[8:9], v[142:143]
	v_pk_fma_f32 v[222:223], v[8:9], v[8:9], v[222:223]
	v_cvt_pk_bf16_f32 v206, v8, v9
	v_lshlrev_b32_e32 v142, 16, v207
	v_and_b32_e32 v143, 0xffff0000, v207
	v_pk_add_f32 v[10:11], v[10:11], v[142:143]
	v_pk_fma_f32 v[222:223], v[10:11], v[10:11], v[222:223]
	v_cvt_pk_bf16_f32 v207, v10, v11
	global_store_dwordx4 v138, v[204:207], s[100:101]
	v_lshlrev_b32_e32 v142, 16, v236
	v_and_b32_e32 v143, 0xffff0000, v236
	v_pk_add_f32 v[4:5], v[4:5], v[142:143]
	v_pk_fma_f32 v[222:223], v[4:5], v[4:5], v[222:223]
	v_cvt_pk_bf16_f32 v236, v4, v5
	v_lshlrev_b32_e32 v142, 16, v237
	v_and_b32_e32 v143, 0xffff0000, v237
	v_pk_add_f32 v[6:7], v[6:7], v[142:143]
	v_pk_fma_f32 v[222:223], v[6:7], v[6:7], v[222:223]
	v_cvt_pk_bf16_f32 v237, v6, v7
	v_lshlrev_b32_e32 v142, 16, v238
	v_and_b32_e32 v143, 0xffff0000, v238
	v_pk_add_f32 v[0:1], v[0:1], v[142:143]
	v_pk_fma_f32 v[222:223], v[0:1], v[0:1], v[222:223]
	v_cvt_pk_bf16_f32 v238, v0, v1
	v_lshlrev_b32_e32 v142, 16, v239
	v_and_b32_e32 v143, 0xffff0000, v239
	v_pk_add_f32 v[2:3], v[2:3], v[142:143]
	v_pk_fma_f32 v[222:223], v[2:3], v[2:3], v[222:223]
	v_cvt_pk_bf16_f32 v239, v2, v3
	global_store_dwordx4 v138, v[236:239], s[100:101] offset:256
	v_add_f32_e32 v12, v222, v223
	ds_bpermute_b32 v125, v140, v124
	ds_bpermute_b32 v109, v140, v108
	ds_bpermute_b32 v93, v140, v92
	ds_bpermute_b32 v77, v140, v76
	ds_bpermute_b32 v61, v140, v60
	ds_bpermute_b32 v45, v140, v44
	ds_bpermute_b32 v29, v140, v28
	ds_bpermute_b32 v13, v140, v12
	s_waitcnt lgkmcnt(0)
	v_add_f32_e32 v124, v124, v125
	v_add_f32_e32 v108, v108, v109
	v_add_f32_e32 v92, v92, v93
	v_add_f32_e32 v76, v76, v77
	v_add_f32_e32 v60, v60, v61
	v_add_f32_e32 v44, v44, v45
	v_add_f32_e32 v28, v28, v29
	v_add_f32_e32 v12, v12, v13
	ds_bpermute_b32 v125, v141, v124
	ds_bpermute_b32 v109, v141, v108
	ds_bpermute_b32 v93, v141, v92
	ds_bpermute_b32 v77, v141, v76
	ds_bpermute_b32 v61, v141, v60
	ds_bpermute_b32 v45, v141, v44
	ds_bpermute_b32 v29, v141, v28
	ds_bpermute_b32 v13, v141, v12
	s_waitcnt lgkmcnt(0)
	v_add_f32_e32 v124, v124, v125
	v_add_f32_e32 v108, v108, v109
	v_add_f32_e32 v92, v92, v93
	v_add_f32_e32 v76, v76, v77
	v_add_f32_e32 v60, v60, v61
	v_add_f32_e32 v44, v44, v45
	v_add_f32_e32 v28, v28, v29
	v_add_f32_e32 v12, v12, v13
	s_and_saveexec_b64 s[98:99], s[4:5]
	global_atomic_add_f32 v139, v124, s[76:77]
	global_atomic_add_f32 v139, v108, s[76:77] offset:64
	global_atomic_add_f32 v139, v92, s[76:77] offset:128
	global_atomic_add_f32 v139, v76, s[76:77] offset:192
	global_atomic_add_f32 v139, v60, s[76:77] offset:512
	global_atomic_add_f32 v139, v44, s[76:77] offset:576
	global_atomic_add_f32 v139, v28, s[76:77] offset:640
	global_atomic_add_f32 v139, v12, s[76:77] offset:704
	s_or_b64 exec, exec, s[98:99]
	s_andn2_b64 vcc, exec, s[6:7]
	s_mov_b64 s[6:7], -1
	s_cbranch_vccnz .LBB0_702
	s_andn2_b64 vcc, exec, s[0:1]
	s_cbranch_vccnz .LBB0_701
	s_barrier
	s_branch .LBB0_701

.LBB0_795:
	s_add_u32 s10, s20, 0xfffc0080
	s_addc_u32 s11, s21, -1
	s_add_i32 s83, 0, 0x10000
	s_cmp_eq_u32 s82, 12
	s_cselect_b32 s25, s15, s11
	s_cselect_b32 s24, s42, s10
	v_add_u32_e32 v138, s83, v141
	s_cselect_b32 s23, s13, s80
	s_cselect_b32 s22, s43, s70
	s_add_i32 s10, 0, 0x14000
	ds_read_b128 v[144:147], v138
	ds_read_b128 v[148:151], v138 offset:1024
	ds_read_b128 v[152:155], v138 offset:2048
	ds_read_b128 v[156:159], v138 offset:3072
	v_add_u32_e32 v138, s10, v141
	ds_read_b128 v[160:163], v138
	ds_read_b128 v[164:167], v138 offset:1024
	ds_read_b128 v[168:171], v138 offset:2048
	ds_read_b128 v[172:175], v138 offset:3072
	v_lshl_add_u64 v[138:139], s[20:21], 0, v[134:135]
	s_add_i32 m0, s29, 0xc000
	ds_read_b128 v[176:179], v143
	ds_read_b128 v[180:183], v143 offset:1024
	ds_read_b128 v[184:187], v143 offset:2048
	ds_read_b128 v[188:191], v143 offset:3072
	ds_read_b128 v[192:195], v143 offset:4096
	ds_read_b128 v[196:199], v143 offset:5120
	ds_read_b128 v[200:203], v143 offset:6144
	ds_read_b128 v[204:207], v143 offset:7168
	global_load_lds_dwordx4 v[138:139], off
	v_lshl_add_u64 v[138:139], s[20:21], 0, v[136:137]
	s_add_i32 m0, s29, 0xe000
	s_nop 0
	global_load_lds_dwordx4 v[138:139], off
	s_waitcnt vmcnt(8)
	s_waitcnt lgkmcnt(0)
	s_barrier
	s_setprio 1
	s_waitcnt lgkmcnt(0)
	v_mfma_f32_16x16x32_bf16 v[124:127], v[144:147], v[176:179], v[124:127]
	v_mfma_f32_16x16x32_bf16 v[120:123], v[152:155], v[176:179], v[120:123]
	v_mfma_f32_16x16x32_bf16 v[108:111], v[144:147], v[184:187], v[108:111]
	v_mfma_f32_16x16x32_bf16 v[104:107], v[152:155], v[184:187], v[104:107]
	v_mfma_f32_16x16x32_bf16 v[92:95], v[144:147], v[192:195], v[92:95]
	v_mfma_f32_16x16x32_bf16 v[88:91], v[152:155], v[192:195], v[88:91]
	v_mfma_f32_16x16x32_bf16 v[76:79], v[144:147], v[200:203], v[76:79]
	v_mfma_f32_16x16x32_bf16 v[72:75], v[152:155], v[200:203], v[72:75]
	v_mfma_f32_16x16x32_bf16 v[124:127], v[148:151], v[180:183], v[124:127]
	v_mfma_f32_16x16x32_bf16 v[120:123], v[156:159], v[180:183], v[120:123]
	v_mfma_f32_16x16x32_bf16 v[108:111], v[148:151], v[188:191], v[108:111]
	v_mfma_f32_16x16x32_bf16 v[104:107], v[156:159], v[188:191], v[104:107]
	v_mfma_f32_16x16x32_bf16 v[92:95], v[148:151], v[196:199], v[92:95]
	v_mfma_f32_16x16x32_bf16 v[88:91], v[156:159], v[196:199], v[88:91]
	v_mfma_f32_16x16x32_bf16 v[76:79], v[148:151], v[204:207], v[76:79]
	v_mfma_f32_16x16x32_bf16 v[72:75], v[156:159], v[204:207], v[72:75]
	s_setprio 0
	s_setprio 1
	v_mfma_f32_16x16x32_bf16 v[116:119], v[160:163], v[176:179], v[116:119]
	v_mfma_f32_16x16x32_bf16 v[112:115], v[168:171], v[176:179], v[112:115]
	v_mfma_f32_16x16x32_bf16 v[100:103], v[160:163], v[184:187], v[100:103]
	v_mfma_f32_16x16x32_bf16 v[96:99], v[168:171], v[184:187], v[96:99]
	v_mfma_f32_16x16x32_bf16 v[84:87], v[160:163], v[192:195], v[84:87]
	v_mfma_f32_16x16x32_bf16 v[80:83], v[168:171], v[192:195], v[80:83]
	v_mfma_f32_16x16x32_bf16 v[68:71], v[160:163], v[200:203], v[68:71]
	v_mfma_f32_16x16x32_bf16 v[64:67], v[168:171], v[200:203], v[64:67]
	v_mfma_f32_16x16x32_bf16 v[116:119], v[164:167], v[180:183], v[116:119]
	v_mfma_f32_16x16x32_bf16 v[112:115], v[172:175], v[180:183], v[112:115]
	v_mfma_f32_16x16x32_bf16 v[100:103], v[164:167], v[188:191], v[100:103]
	v_mfma_f32_16x16x32_bf16 v[96:99], v[172:175], v[188:191], v[96:99]
	v_mfma_f32_16x16x32_bf16 v[84:87], v[164:167], v[196:199], v[84:87]
	v_mfma_f32_16x16x32_bf16 v[80:83], v[172:175], v[196:199], v[80:83]
	v_mfma_f32_16x16x32_bf16 v[68:71], v[164:167], v[204:207], v[68:71]
	v_mfma_f32_16x16x32_bf16 v[64:67], v[172:175], v[204:207], v[64:67]
	s_setprio 0
	s_barrier
	s_add_i32 s11, s83, s28
	v_lshl_add_u64 v[138:139], s[22:23], 0, v[208:209]
	s_mov_b32 m0, s11
	ds_read_b128 v[176:179], v143 offset:16384
	ds_read_b128 v[180:183], v143 offset:17408
	ds_read_b128 v[184:187], v143 offset:18432
	ds_read_b128 v[188:191], v143 offset:19456
	ds_read_b128 v[192:195], v143 offset:20480
	ds_read_b128 v[196:199], v143 offset:21504
	ds_read_b128 v[200:203], v143 offset:22528
	ds_read_b128 v[204:207], v143 offset:23552
	global_load_lds_dwordx4 v[138:139], off
	s_add_i32 m0, s11, 0x2000
	s_add_u32 vcc_lo, s22, 0x40000
	v_lshl_add_u64 v[222:223], s[22:23], 0, v[128:129]
	s_addc_u32 vcc_hi, s23, 0
	s_add_i32 s10, s10, s28
	global_load_lds_dwordx4 v[222:223], off
	v_lshl_add_u64 v[224:225], vcc, 0, v[208:209]
	s_mov_b32 m0, s10
	v_lshl_add_u64 v[236:237], s[24:25], 0, v[130:131]
	global_load_lds_dwordx4 v[224:225], off
	v_lshl_add_u64 v[224:225], vcc, 0, v[128:129]
	s_add_i32 m0, s10, 0x2000
	s_nop 0
	global_load_lds_dwordx4 v[224:225], off
	v_lshl_add_u64 v[224:225], s[24:25], 0, v[132:133]
	s_mov_b32 m0, s29
	s_nop 0
	global_load_lds_dwordx4 v[224:225], off
	s_mov_b32 m0, s30
	s_nop 0
	global_load_lds_dwordx4 v[236:237], off
	s_waitcnt vmcnt(8)
	s_waitcnt lgkmcnt(0)
	s_barrier
	s_setprio 1
	s_waitcnt lgkmcnt(0)
	v_mfma_f32_16x16x32_bf16 v[60:63], v[144:147], v[176:179], v[60:63]
	v_mfma_f32_16x16x32_bf16 v[56:59], v[152:155], v[176:179], v[56:59]
	v_mfma_f32_16x16x32_bf16 v[44:47], v[144:147], v[184:187], v[44:47]
	v_mfma_f32_16x16x32_bf16 v[40:43], v[152:155], v[184:187], v[40:43]
	v_mfma_f32_16x16x32_bf16 v[28:31], v[144:147], v[192:195], v[28:31]
	v_mfma_f32_16x16x32_bf16 v[24:27], v[152:155], v[192:195], v[24:27]
	v_mfma_f32_16x16x32_bf16 v[12:15], v[144:147], v[200:203], v[12:15]
	v_mfma_f32_16x16x32_bf16 v[8:11], v[152:155], v[200:203], v[8:11]
	v_mfma_f32_16x16x32_bf16 v[60:63], v[148:151], v[180:183], v[60:63]
	v_mfma_f32_16x16x32_bf16 v[56:59], v[156:159], v[180:183], v[56:59]
	v_mfma_f32_16x16x32_bf16 v[44:47], v[148:151], v[188:191], v[44:47]
	v_mfma_f32_16x16x32_bf16 v[40:43], v[156:159], v[188:191], v[40:43]
	v_mfma_f32_16x16x32_bf16 v[28:31], v[148:151], v[196:199], v[28:31]
	v_mfma_f32_16x16x32_bf16 v[24:27], v[156:159], v[196:199], v[24:27]
	v_mfma_f32_16x16x32_bf16 v[12:15], v[148:151], v[204:207], v[12:15]
	v_mfma_f32_16x16x32_bf16 v[8:11], v[156:159], v[204:207], v[8:11]
	s_setprio 0
	s_setprio 1
	v_mfma_f32_16x16x32_bf16 v[52:55], v[160:163], v[176:179], v[52:55]
	v_mfma_f32_16x16x32_bf16 v[48:51], v[168:171], v[176:179], v[48:51]
	v_mfma_f32_16x16x32_bf16 v[36:39], v[160:163], v[184:187], v[36:39]
	v_mfma_f32_16x16x32_bf16 v[32:35], v[168:171], v[184:187], v[32:35]
	v_mfma_f32_16x16x32_bf16 v[20:23], v[160:163], v[192:195], v[20:23]
	v_mfma_f32_16x16x32_bf16 v[16:19], v[168:171], v[192:195], v[16:19]
	v_mfma_f32_16x16x32_bf16 v[4:7], v[160:163], v[200:203], v[4:7]
	v_mfma_f32_16x16x32_bf16 v[0:3], v[168:171], v[200:203], v[0:3]
	v_mfma_f32_16x16x32_bf16 v[52:55], v[164:167], v[180:183], v[52:55]
	v_mfma_f32_16x16x32_bf16 v[48:51], v[172:175], v[180:183], v[48:51]
	v_mfma_f32_16x16x32_bf16 v[36:39], v[164:167], v[188:191], v[36:39]
	v_mfma_f32_16x16x32_bf16 v[32:35], v[172:175], v[188:191], v[32:35]
	v_mfma_f32_16x16x32_bf16 v[20:23], v[164:167], v[196:199], v[20:23]
	v_mfma_f32_16x16x32_bf16 v[16:19], v[172:175], v[196:199], v[16:19]
	v_mfma_f32_16x16x32_bf16 v[4:7], v[164:167], v[204:207], v[4:7]
	v_mfma_f32_16x16x32_bf16 v[0:3], v[172:175], v[204:207], v[0:3]
	s_setprio 0
	s_barrier
	s_add_i32 s10, 0, 0x18000
	s_add_i32 s11, 0, 0x1c000
	v_add_u32_e32 v156, s10, v141
	v_add_u32_e32 v172, s11, v141
	ds_read_b128 v[144:147], v156
	ds_read_b128 v[148:151], v156 offset:1024
	ds_read_b128 v[152:155], v156 offset:2048
	ds_read_b128 v[156:159], v156 offset:3072
	ds_read_b128 v[160:163], v172
	ds_read_b128 v[164:167], v172 offset:1024
	ds_read_b128 v[168:171], v172 offset:2048
	ds_read_b128 v[172:175], v172 offset:3072
	s_add_u32 s24, s24, 0x40000
	s_addc_u32 s25, s25, 0
	s_mov_b32 m0, s31
	v_lshl_add_u64 v[238:239], s[24:25], 0, v[132:133]
	ds_read_b128 v[176:179], v143 offset:32768
	ds_read_b128 v[180:183], v143 offset:33792
	ds_read_b128 v[184:187], v143 offset:34816
	ds_read_b128 v[188:191], v143 offset:35840
	ds_read_b128 v[192:195], v143 offset:36864
	ds_read_b128 v[196:199], v143 offset:37888
	ds_read_b128 v[200:203], v143 offset:38912
	ds_read_b128 v[204:207], v143 offset:39936
	global_load_lds_dwordx4 v[238:239], off
	v_lshl_add_u64 v[238:239], s[24:25], 0, v[130:131]
	s_mov_b32 m0, s34
	s_nop 0
	global_load_lds_dwordx4 v[238:239], off
	s_waitcnt vmcnt(8)
	s_waitcnt lgkmcnt(0)
	s_barrier
	s_setprio 1
	s_waitcnt lgkmcnt(0)
	v_mfma_f32_16x16x32_bf16 v[124:127], v[144:147], v[176:179], v[124:127]
	v_mfma_f32_16x16x32_bf16 v[120:123], v[152:155], v[176:179], v[120:123]
	v_mfma_f32_16x16x32_bf16 v[108:111], v[144:147], v[184:187], v[108:111]
	v_mfma_f32_16x16x32_bf16 v[104:107], v[152:155], v[184:187], v[104:107]
	v_mfma_f32_16x16x32_bf16 v[92:95], v[144:147], v[192:195], v[92:95]
	v_mfma_f32_16x16x32_bf16 v[88:91], v[152:155], v[192:195], v[88:91]
	v_mfma_f32_16x16x32_bf16 v[76:79], v[144:147], v[200:203], v[76:79]
	v_mfma_f32_16x16x32_bf16 v[72:75], v[152:155], v[200:203], v[72:75]
	v_mfma_f32_16x16x32_bf16 v[124:127], v[148:151], v[180:183], v[124:127]
	v_mfma_f32_16x16x32_bf16 v[120:123], v[156:159], v[180:183], v[120:123]
	v_mfma_f32_16x16x32_bf16 v[108:111], v[148:151], v[188:191], v[108:111]
	v_mfma_f32_16x16x32_bf16 v[104:107], v[156:159], v[188:191], v[104:107]
	v_mfma_f32_16x16x32_bf16 v[92:95], v[148:151], v[196:199], v[92:95]
	v_mfma_f32_16x16x32_bf16 v[88:91], v[156:159], v[196:199], v[88:91]
	v_mfma_f32_16x16x32_bf16 v[76:79], v[148:151], v[204:207], v[76:79]
	v_mfma_f32_16x16x32_bf16 v[72:75], v[156:159], v[204:207], v[72:75]
	s_setprio 0
	s_setprio 1
	v_mfma_f32_16x16x32_bf16 v[116:119], v[160:163], v[176:179], v[116:119]
	v_mfma_f32_16x16x32_bf16 v[112:115], v[168:171], v[176:179], v[112:115]
	v_mfma_f32_16x16x32_bf16 v[100:103], v[160:163], v[184:187], v[100:103]
	v_mfma_f32_16x16x32_bf16 v[96:99], v[168:171], v[184:187], v[96:99]
	v_mfma_f32_16x16x32_bf16 v[84:87], v[160:163], v[192:195], v[84:87]
	v_mfma_f32_16x16x32_bf16 v[80:83], v[168:171], v[192:195], v[80:83]
	v_mfma_f32_16x16x32_bf16 v[68:71], v[160:163], v[200:203], v[68:71]
	v_mfma_f32_16x16x32_bf16 v[64:67], v[168:171], v[200:203], v[64:67]
	v_mfma_f32_16x16x32_bf16 v[116:119], v[164:167], v[180:183], v[116:119]
	v_mfma_f32_16x16x32_bf16 v[112:115], v[172:175], v[180:183], v[112:115]
	v_mfma_f32_16x16x32_bf16 v[100:103], v[164:167], v[188:191], v[100:103]
	v_mfma_f32_16x16x32_bf16 v[96:99], v[172:175], v[188:191], v[96:99]
	v_mfma_f32_16x16x32_bf16 v[84:87], v[164:167], v[196:199], v[84:87]
	v_mfma_f32_16x16x32_bf16 v[80:83], v[172:175], v[196:199], v[80:83]
	v_mfma_f32_16x16x32_bf16 v[68:71], v[164:167], v[204:207], v[68:71]
	v_mfma_f32_16x16x32_bf16 v[64:67], v[172:175], v[204:207], v[64:67]
	s_setprio 0
	s_barrier
	s_add_i32 s10, s10, s28
	v_lshl_add_u64 v[138:139], v[138:139], 0, s[94:95]
	s_mov_b32 m0, s10
	ds_read_b128 v[176:179], v143 offset:49152
	ds_read_b128 v[180:183], v143 offset:50176
	ds_read_b128 v[184:187], v143 offset:51200
	ds_read_b128 v[188:191], v143 offset:52224
	ds_read_b128 v[192:195], v143 offset:53248
	ds_read_b128 v[196:199], v143 offset:54272
	ds_read_b128 v[200:203], v143 offset:55296
	ds_read_b128 v[204:207], v143 offset:56320
	global_load_lds_dwordx4 v[138:139], off
	s_add_i32 m0, s10, 0x2000
	s_add_u32 s22, s22, 0x40080
	v_lshl_add_u64 v[138:139], v[222:223], 0, s[94:95]
	s_addc_u32 s23, s23, 0
	s_add_i32 s10, s11, s28
	global_load_lds_dwordx4 v[138:139], off
	v_lshl_add_u64 v[138:139], s[22:23], 0, v[208:209]
	s_mov_b32 m0, s10
	s_nop 0
	global_load_lds_dwordx4 v[138:139], off
	v_lshl_add_u64 v[138:139], s[22:23], 0, v[128:129]
	s_add_i32 m0, s10, 0x2000
	s_nop 0
	global_load_lds_dwordx4 v[138:139], off
	v_lshl_add_u64 v[138:139], v[224:225], 0, s[94:95]
	s_mov_b32 m0, s35
	s_nop 0
	global_load_lds_dwordx4 v[138:139], off
	v_lshl_add_u64 v[138:139], v[236:237], 0, s[94:95]
	s_mov_b32 m0, s36
	s_nop 0
	global_load_lds_dwordx4 v[138:139], off
	s_waitcnt vmcnt(8)
	s_waitcnt lgkmcnt(0)
	s_barrier
	s_setprio 1
	s_waitcnt lgkmcnt(0)
	v_mfma_f32_16x16x32_bf16 v[60:63], v[144:147], v[176:179], v[60:63]
	v_mfma_f32_16x16x32_bf16 v[56:59], v[152:155], v[176:179], v[56:59]
	v_mfma_f32_16x16x32_bf16 v[44:47], v[144:147], v[184:187], v[44:47]
	v_mfma_f32_16x16x32_bf16 v[40:43], v[152:155], v[184:187], v[40:43]
	v_mfma_f32_16x16x32_bf16 v[28:31], v[144:147], v[192:195], v[28:31]
	v_mfma_f32_16x16x32_bf16 v[24:27], v[152:155], v[192:195], v[24:27]
	v_mfma_f32_16x16x32_bf16 v[12:15], v[144:147], v[200:203], v[12:15]
	v_mfma_f32_16x16x32_bf16 v[8:11], v[152:155], v[200:203], v[8:11]
	v_mfma_f32_16x16x32_bf16 v[60:63], v[148:151], v[180:183], v[60:63]
	v_mfma_f32_16x16x32_bf16 v[56:59], v[156:159], v[180:183], v[56:59]
	v_mfma_f32_16x16x32_bf16 v[44:47], v[148:151], v[188:191], v[44:47]
	v_mfma_f32_16x16x32_bf16 v[40:43], v[156:159], v[188:191], v[40:43]
	v_mfma_f32_16x16x32_bf16 v[28:31], v[148:151], v[196:199], v[28:31]
	v_mfma_f32_16x16x32_bf16 v[24:27], v[156:159], v[196:199], v[24:27]
	v_mfma_f32_16x16x32_bf16 v[12:15], v[148:151], v[204:207], v[12:15]
	v_mfma_f32_16x16x32_bf16 v[8:11], v[156:159], v[204:207], v[8:11]
	s_setprio 0
	s_setprio 1
	v_mfma_f32_16x16x32_bf16 v[52:55], v[160:163], v[176:179], v[52:55]
	v_mfma_f32_16x16x32_bf16 v[48:51], v[168:171], v[176:179], v[48:51]
	v_mfma_f32_16x16x32_bf16 v[36:39], v[160:163], v[184:187], v[36:39]
	v_mfma_f32_16x16x32_bf16 v[32:35], v[168:171], v[184:187], v[32:35]
	v_mfma_f32_16x16x32_bf16 v[20:23], v[160:163], v[192:195], v[20:23]
	v_mfma_f32_16x16x32_bf16 v[16:19], v[168:171], v[192:195], v[16:19]
	v_mfma_f32_16x16x32_bf16 v[4:7], v[160:163], v[200:203], v[4:7]
	v_mfma_f32_16x16x32_bf16 v[0:3], v[168:171], v[200:203], v[0:3]
	v_mfma_f32_16x16x32_bf16 v[52:55], v[164:167], v[180:183], v[52:55]
	v_mfma_f32_16x16x32_bf16 v[48:51], v[172:175], v[180:183], v[48:51]
	v_mfma_f32_16x16x32_bf16 v[36:39], v[164:167], v[188:191], v[36:39]
	v_mfma_f32_16x16x32_bf16 v[32:35], v[172:175], v[188:191], v[32:35]
	v_mfma_f32_16x16x32_bf16 v[20:23], v[164:167], v[196:199], v[20:23]
	v_mfma_f32_16x16x32_bf16 v[16:19], v[172:175], v[196:199], v[16:19]
	v_mfma_f32_16x16x32_bf16 v[4:7], v[164:167], v[204:207], v[4:7]
	v_mfma_f32_16x16x32_bf16 v[0:3], v[172:175], v[204:207], v[0:3]
	s_setprio 0
	s_barrier
	s_add_i32 s82, s82, 2
	s_add_u32 s20, s20, 0x100
	s_addc_u32 s21, s21, 0
	s_add_u32 s70, s70, 0x100
	s_addc_u32 s80, s80, 0
	s_cmp_gt_u32 s82, 13
	s_cbranch_scc0 .LBB0_795
	v_lshl_add_u32 v138, s40, 8, v140
	v_ashrrev_i32_e32 v139, 31, v138
	v_lshl_add_u64 v[146:147], v[138:139], 2, s[76:77]
	global_load_dword v160, v[146:147], off
	global_load_dword v161, v[146:147], off offset:64
	global_load_dword v162, v[146:147], off offset:128
	global_load_dword v163, v[146:147], off offset:192
	global_load_dword v164, v[146:147], off offset:512
	global_load_dword v165, v[146:147], off offset:576
	global_load_dword v166, v[146:147], off offset:640
	global_load_dword v167, v[146:147], off offset:704
	s_and_b64 vcc, exec, s[6:7]
	s_cbranch_vccz .LBB0_798
	s_barrier
.LBB0_798:
	v_lshl_or_b32 v144, s41, 8, v142
	v_ashrrev_i32_e32 v145, 31, v144
	v_lshlrev_b64 v[148:149], 13, v[138:139]
	s_mov_b64 s[20:21], -1
	s_waitcnt vmcnt(0)
	v_fmamk_f32 v146, v160, 0x3a800000, v228
	v_cmp_gt_f32_e32 vcc, s69, v146
	v_mul_f32_e32 v147, 0x4b800000, v146
	s_nop 0
	v_cndmask_b32_e32 v146, v146, v147, vcc
	v_rsq_f32_e32 v146, v146
	s_nop 0
	v_mul_f32_e32 v147, 0x45800000, v146
	v_cndmask_b32_e32 v146, v146, v147, vcc
	v_pk_mul_f32 v[126:127], v[126:127], v[146:147] op_sel_hi:[1,0]
	v_pk_mul_f32 v[124:125], v[124:125], v[146:147] op_sel_hi:[1,0]
	v_pk_mul_f32 v[120:121], v[120:121], v[146:147] op_sel_hi:[1,0]
	v_pk_mul_f32 v[122:123], v[122:123], v[146:147] op_sel_hi:[1,0]
	v_max_f32_e32 v124, 0, v124
	v_max_f32_e32 v120, 0, v120
	v_max_f32_e32 v125, 0, v125
	v_max_f32_e32 v121, 0, v121
	v_max_f32_e32 v126, 0, v126
	v_max_f32_e32 v127, 0, v127
	v_pk_mul_f32 v[124:125], v[124:125], v[124:125]
	v_pk_mul_f32 v[120:121], v[120:121], v[120:121]
	v_max_f32_e32 v122, 0, v122
	v_max_f32_e32 v123, 0, v123
	v_pk_mul_f32 v[126:127], v[126:127], v[126:127]
	v_pk_mul_f32 v[150:151], v[122:123], v[122:123]
	v_cvt_pk_bf16_f32 v122, v124, v125
	v_cvt_pk_bf16_f32 v123, v126, v127
	v_cvt_pk_bf16_f32 v124, v120, v121
	v_lshl_add_u64 v[126:127], s[88:89], 0, v[148:149]
	v_lshlrev_b64 v[120:121], 1, v[144:145]
	v_pk_mul_f32 v[112:113], v[112:113], v[146:147] op_sel_hi:[1,0]
	v_cvt_pk_bf16_f32 v125, v150, v151
	v_lshl_add_u64 v[126:127], v[126:127], 0, v[120:121]
	v_pk_mul_f32 v[118:119], v[118:119], v[146:147] op_sel_hi:[1,0]
	v_pk_mul_f32 v[116:117], v[116:117], v[146:147] op_sel_hi:[1,0]
	v_pk_mul_f32 v[114:115], v[114:115], v[146:147] op_sel_hi:[1,0]
	v_max_f32_e32 v112, 0, v112
	v_max_f32_e32 v113, 0, v113
	global_store_dwordx4 v[126:127], v[122:125], off
	v_max_f32_e32 v116, 0, v116
	v_max_f32_e32 v117, 0, v117
	v_pk_mul_f32 v[122:123], v[112:113], v[112:113]
	v_max_f32_e32 v112, 0, v118
	v_max_f32_e32 v114, 0, v114
	v_max_f32_e32 v113, 0, v119
	v_max_f32_e32 v115, 0, v115
	v_pk_mul_f32 v[116:117], v[116:117], v[116:117]
	v_pk_mul_f32 v[118:119], v[112:113], v[112:113]
	v_pk_mul_f32 v[124:125], v[114:115], v[114:115]
	v_cvt_pk_bf16_f32 v112, v116, v117
	v_cvt_pk_bf16_f32 v113, v118, v119
	v_cvt_pk_bf16_f32 v114, v122, v123
	v_cvt_pk_bf16_f32 v115, v124, v125
	global_store_dwordx4 v[126:127], v[112:115], off offset:256
	s_nop 1
	v_or_b32_e32 v112, 16, v138
	v_ashrrev_i32_e32 v113, 31, v112
	v_lshlrev_b64 v[112:113], 13, v[112:113]
	v_fmamk_f32 v114, v161, 0x3a800000, v228
	v_cmp_gt_f32_e32 vcc, s69, v114
	v_mul_f32_e32 v115, 0x4b800000, v114
	s_nop 0
	v_cndmask_b32_e32 v114, v114, v115, vcc
	v_rsq_f32_e32 v114, v114
	s_nop 0
	v_mul_f32_e32 v115, 0x45800000, v114
	v_cndmask_b32_e32 v114, v114, v115, vcc
	v_pk_mul_f32 v[108:109], v[108:109], v[114:115] op_sel_hi:[1,0]
	v_pk_mul_f32 v[104:105], v[104:105], v[114:115] op_sel_hi:[1,0]
	v_pk_mul_f32 v[110:111], v[110:111], v[114:115] op_sel_hi:[1,0]
	v_pk_mul_f32 v[106:107], v[106:107], v[114:115] op_sel_hi:[1,0]
	v_max_f32_e32 v108, 0, v108
	v_max_f32_e32 v104, 0, v104
	v_max_f32_e32 v109, 0, v109
	v_max_f32_e32 v105, 0, v105
	v_pk_mul_f32 v[108:109], v[108:109], v[108:109]
	v_pk_mul_f32 v[116:117], v[104:105], v[104:105]
	v_max_f32_e32 v104, 0, v110
	v_max_f32_e32 v106, 0, v106
	v_max_f32_e32 v105, 0, v111
	v_max_f32_e32 v107, 0, v107
	v_pk_mul_f32 v[110:111], v[104:105], v[104:105]
	v_pk_mul_f32 v[118:119], v[106:107], v[106:107]
	v_cvt_pk_bf16_f32 v104, v108, v109
	v_lshl_add_u64 v[108:109], s[88:89], 0, v[112:113]
	v_pk_mul_f32 v[96:97], v[96:97], v[114:115] op_sel_hi:[1,0]
	v_cvt_pk_bf16_f32 v105, v110, v111
	v_cvt_pk_bf16_f32 v106, v116, v117
	v_cvt_pk_bf16_f32 v107, v118, v119
	v_lshl_add_u64 v[108:109], v[108:109], 0, v[120:121]
	v_pk_mul_f32 v[102:103], v[102:103], v[114:115] op_sel_hi:[1,0]
	v_pk_mul_f32 v[100:101], v[100:101], v[114:115] op_sel_hi:[1,0]
	v_pk_mul_f32 v[98:99], v[98:99], v[114:115] op_sel_hi:[1,0]
	v_max_f32_e32 v96, 0, v96
	v_max_f32_e32 v97, 0, v97
	global_store_dwordx4 v[108:109], v[104:107], off
	v_max_f32_e32 v100, 0, v100
	v_max_f32_e32 v101, 0, v101
	v_pk_mul_f32 v[104:105], v[96:97], v[96:97]
	v_max_f32_e32 v96, 0, v102
	v_max_f32_e32 v98, 0, v98
	v_max_f32_e32 v97, 0, v103
	v_max_f32_e32 v99, 0, v99
	v_pk_mul_f32 v[100:101], v[100:101], v[100:101]
	v_pk_mul_f32 v[102:103], v[96:97], v[96:97]
	v_pk_mul_f32 v[106:107], v[98:99], v[98:99]
	v_cvt_pk_bf16_f32 v96, v100, v101
	v_cvt_pk_bf16_f32 v97, v102, v103
	v_cvt_pk_bf16_f32 v98, v104, v105
	v_cvt_pk_bf16_f32 v99, v106, v107
	global_store_dwordx4 v[108:109], v[96:99], off offset:256
	s_nop 1
	v_or_b32_e32 v96, 32, v138
	v_ashrrev_i32_e32 v97, 31, v96
	v_lshlrev_b64 v[96:97], 13, v[96:97]
	v_fmamk_f32 v98, v162, 0x3a800000, v228
	v_cmp_gt_f32_e32 vcc, s69, v98
	v_mul_f32_e32 v99, 0x4b800000, v98
	s_nop 0
	v_cndmask_b32_e32 v98, v98, v99, vcc
	v_rsq_f32_e32 v98, v98
	s_nop 0
	v_mul_f32_e32 v99, 0x45800000, v98
	v_cndmask_b32_e32 v98, v98, v99, vcc
	v_pk_mul_f32 v[92:93], v[92:93], v[98:99] op_sel_hi:[1,0]
	v_pk_mul_f32 v[88:89], v[88:89], v[98:99] op_sel_hi:[1,0]
	v_pk_mul_f32 v[94:95], v[94:95], v[98:99] op_sel_hi:[1,0]
	v_pk_mul_f32 v[90:91], v[90:91], v[98:99] op_sel_hi:[1,0]
	v_max_f32_e32 v92, 0, v92
	v_max_f32_e32 v88, 0, v88
	v_max_f32_e32 v93, 0, v93
	v_max_f32_e32 v89, 0, v89
	v_pk_mul_f32 v[92:93], v[92:93], v[92:93]
	v_pk_mul_f32 v[100:101], v[88:89], v[88:89]
	v_max_f32_e32 v88, 0, v94
	v_max_f32_e32 v90, 0, v90
	v_max_f32_e32 v89, 0, v95
	v_max_f32_e32 v91, 0, v91
	v_pk_mul_f32 v[94:95], v[88:89], v[88:89]
	v_pk_mul_f32 v[102:103], v[90:91], v[90:91]
	v_cvt_pk_bf16_f32 v88, v92, v93
	v_lshl_add_u64 v[92:93], s[88:89], 0, v[96:97]
	v_pk_mul_f32 v[80:81], v[80:81], v[98:99] op_sel_hi:[1,0]
	v_cvt_pk_bf16_f32 v89, v94, v95
	v_cvt_pk_bf16_f32 v90, v100, v101
	v_cvt_pk_bf16_f32 v91, v102, v103
	v_lshl_add_u64 v[92:93], v[92:93], 0, v[120:121]
	v_pk_mul_f32 v[86:87], v[86:87], v[98:99] op_sel_hi:[1,0]
	v_pk_mul_f32 v[84:85], v[84:85], v[98:99] op_sel_hi:[1,0]
	v_pk_mul_f32 v[82:83], v[82:83], v[98:99] op_sel_hi:[1,0]
	v_max_f32_e32 v80, 0, v80
	v_max_f32_e32 v81, 0, v81
	global_store_dwordx4 v[92:93], v[88:91], off
	v_max_f32_e32 v84, 0, v84
	v_max_f32_e32 v85, 0, v85
	v_pk_mul_f32 v[88:89], v[80:81], v[80:81]
	v_max_f32_e32 v80, 0, v86
	v_max_f32_e32 v82, 0, v82
	v_max_f32_e32 v81, 0, v87
	v_max_f32_e32 v83, 0, v83
	v_pk_mul_f32 v[84:85], v[84:85], v[84:85]
	v_pk_mul_f32 v[86:87], v[80:81], v[80:81]
	v_pk_mul_f32 v[90:91], v[82:83], v[82:83]
	v_cvt_pk_bf16_f32 v80, v84, v85
	v_cvt_pk_bf16_f32 v81, v86, v87
	v_cvt_pk_bf16_f32 v82, v88, v89
	v_cvt_pk_bf16_f32 v83, v90, v91
	global_store_dwordx4 v[92:93], v[80:83], off offset:256
	s_nop 1
	v_or_b32_e32 v80, 48, v138
	v_ashrrev_i32_e32 v81, 31, v80
	v_lshlrev_b64 v[80:81], 13, v[80:81]
	v_fmamk_f32 v82, v163, 0x3a800000, v228
	v_cmp_gt_f32_e32 vcc, s69, v82
	v_mul_f32_e32 v83, 0x4b800000, v82
	s_nop 0
	v_cndmask_b32_e32 v82, v82, v83, vcc
	v_rsq_f32_e32 v82, v82
	s_nop 0
	v_mul_f32_e32 v83, 0x45800000, v82
	v_cndmask_b32_e32 v82, v82, v83, vcc
	v_pk_mul_f32 v[76:77], v[76:77], v[82:83] op_sel_hi:[1,0]
	v_pk_mul_f32 v[72:73], v[72:73], v[82:83] op_sel_hi:[1,0]
	v_pk_mul_f32 v[78:79], v[78:79], v[82:83] op_sel_hi:[1,0]
	v_pk_mul_f32 v[74:75], v[74:75], v[82:83] op_sel_hi:[1,0]
	v_max_f32_e32 v76, 0, v76
	v_max_f32_e32 v72, 0, v72
	v_max_f32_e32 v77, 0, v77
	v_max_f32_e32 v73, 0, v73
	v_pk_mul_f32 v[76:77], v[76:77], v[76:77]
	v_pk_mul_f32 v[84:85], v[72:73], v[72:73]
	v_max_f32_e32 v72, 0, v78
	v_max_f32_e32 v74, 0, v74
	v_max_f32_e32 v73, 0, v79
	v_max_f32_e32 v75, 0, v75
	v_pk_mul_f32 v[78:79], v[72:73], v[72:73]
	v_pk_mul_f32 v[86:87], v[74:75], v[74:75]
	v_cvt_pk_bf16_f32 v72, v76, v77
	v_lshl_add_u64 v[76:77], s[88:89], 0, v[80:81]
	v_pk_mul_f32 v[64:65], v[64:65], v[82:83] op_sel_hi:[1,0]
	v_cvt_pk_bf16_f32 v73, v78, v79
	v_cvt_pk_bf16_f32 v74, v84, v85
	v_cvt_pk_bf16_f32 v75, v86, v87
	v_lshl_add_u64 v[76:77], v[76:77], 0, v[120:121]
	v_pk_mul_f32 v[70:71], v[70:71], v[82:83] op_sel_hi:[1,0]
	v_pk_mul_f32 v[68:69], v[68:69], v[82:83] op_sel_hi:[1,0]
	v_pk_mul_f32 v[66:67], v[66:67], v[82:83] op_sel_hi:[1,0]
	v_max_f32_e32 v64, 0, v64
	v_max_f32_e32 v65, 0, v65
	global_store_dwordx4 v[76:77], v[72:75], off
	v_max_f32_e32 v68, 0, v68
	v_max_f32_e32 v69, 0, v69
	v_pk_mul_f32 v[72:73], v[64:65], v[64:65]
	v_max_f32_e32 v64, 0, v70
	v_max_f32_e32 v66, 0, v66
	v_max_f32_e32 v65, 0, v71
	v_max_f32_e32 v67, 0, v67
	v_pk_mul_f32 v[68:69], v[68:69], v[68:69]
	v_pk_mul_f32 v[70:71], v[64:65], v[64:65]
	v_pk_mul_f32 v[74:75], v[66:67], v[66:67]
	v_cvt_pk_bf16_f32 v64, v68, v69
	v_cvt_pk_bf16_f32 v65, v70, v71
	v_cvt_pk_bf16_f32 v66, v72, v73
	v_cvt_pk_bf16_f32 v67, v74, v75
	global_store_dwordx4 v[76:77], v[64:67], off offset:256
	s_nop 1
	v_add_u32_e32 v64, 0x80, v138
	v_ashrrev_i32_e32 v65, 31, v64
	v_lshlrev_b64 v[64:65], 13, v[64:65]
	v_fmamk_f32 v66, v164, 0x3a800000, v228
	v_cmp_gt_f32_e32 vcc, s69, v66
	v_mul_f32_e32 v67, 0x4b800000, v66
	s_nop 0
	v_cndmask_b32_e32 v66, v66, v67, vcc
	v_rsq_f32_e32 v66, v66
	s_nop 0
	v_mul_f32_e32 v67, 0x45800000, v66
	v_cndmask_b32_e32 v66, v66, v67, vcc
	v_pk_mul_f32 v[60:61], v[60:61], v[66:67] op_sel_hi:[1,0]
	v_pk_mul_f32 v[56:57], v[56:57], v[66:67] op_sel_hi:[1,0]
	v_pk_mul_f32 v[62:63], v[62:63], v[66:67] op_sel_hi:[1,0]
	v_pk_mul_f32 v[58:59], v[58:59], v[66:67] op_sel_hi:[1,0]
	v_max_f32_e32 v60, 0, v60
	v_max_f32_e32 v56, 0, v56
	v_max_f32_e32 v61, 0, v61
	v_max_f32_e32 v57, 0, v57
	v_pk_mul_f32 v[60:61], v[60:61], v[60:61]
	v_pk_mul_f32 v[68:69], v[56:57], v[56:57]
	v_max_f32_e32 v56, 0, v62
	v_max_f32_e32 v58, 0, v58
	v_max_f32_e32 v57, 0, v63
	v_max_f32_e32 v59, 0, v59
	v_pk_mul_f32 v[62:63], v[56:57], v[56:57]
	v_pk_mul_f32 v[70:71], v[58:59], v[58:59]
	v_cvt_pk_bf16_f32 v56, v60, v61
	v_lshl_add_u64 v[60:61], s[88:89], 0, v[64:65]
	v_pk_mul_f32 v[48:49], v[48:49], v[66:67] op_sel_hi:[1,0]
	v_cvt_pk_bf16_f32 v57, v62, v63
	v_cvt_pk_bf16_f32 v58, v68, v69
	v_cvt_pk_bf16_f32 v59, v70, v71
	v_lshl_add_u64 v[60:61], v[60:61], 0, v[120:121]
	v_pk_mul_f32 v[54:55], v[54:55], v[66:67] op_sel_hi:[1,0]
	v_pk_mul_f32 v[52:53], v[52:53], v[66:67] op_sel_hi:[1,0]
	v_pk_mul_f32 v[50:51], v[50:51], v[66:67] op_sel_hi:[1,0]
	v_max_f32_e32 v48, 0, v48
	v_max_f32_e32 v49, 0, v49
	global_store_dwordx4 v[60:61], v[56:59], off
	v_max_f32_e32 v52, 0, v52
	v_max_f32_e32 v53, 0, v53
	v_pk_mul_f32 v[56:57], v[48:49], v[48:49]
	v_max_f32_e32 v48, 0, v54
	v_max_f32_e32 v50, 0, v50
	v_max_f32_e32 v49, 0, v55
	v_max_f32_e32 v51, 0, v51
	v_pk_mul_f32 v[52:53], v[52:53], v[52:53]
	v_pk_mul_f32 v[54:55], v[48:49], v[48:49]
	v_pk_mul_f32 v[58:59], v[50:51], v[50:51]
	v_cvt_pk_bf16_f32 v48, v52, v53
	v_cvt_pk_bf16_f32 v49, v54, v55
	v_cvt_pk_bf16_f32 v50, v56, v57
	v_cvt_pk_bf16_f32 v51, v58, v59
	global_store_dwordx4 v[60:61], v[48:51], off offset:256
	s_nop 1
	v_add_u32_e32 v48, 0x90, v138
	v_ashrrev_i32_e32 v49, 31, v48
	v_lshlrev_b64 v[48:49], 13, v[48:49]
	v_fmamk_f32 v50, v165, 0x3a800000, v228
	v_cmp_gt_f32_e32 vcc, s69, v50
	v_mul_f32_e32 v51, 0x4b800000, v50
	s_nop 0
	v_cndmask_b32_e32 v50, v50, v51, vcc
	v_rsq_f32_e32 v50, v50
	s_nop 0
	v_mul_f32_e32 v51, 0x45800000, v50
	v_cndmask_b32_e32 v50, v50, v51, vcc
	v_pk_mul_f32 v[44:45], v[44:45], v[50:51] op_sel_hi:[1,0]
	v_pk_mul_f32 v[40:41], v[40:41], v[50:51] op_sel_hi:[1,0]
	v_pk_mul_f32 v[46:47], v[46:47], v[50:51] op_sel_hi:[1,0]
	v_pk_mul_f32 v[42:43], v[42:43], v[50:51] op_sel_hi:[1,0]
	v_max_f32_e32 v44, 0, v44
	v_max_f32_e32 v40, 0, v40
	v_max_f32_e32 v45, 0, v45
	v_max_f32_e32 v41, 0, v41
	v_pk_mul_f32 v[44:45], v[44:45], v[44:45]
	v_pk_mul_f32 v[52:53], v[40:41], v[40:41]
	v_max_f32_e32 v40, 0, v46
	v_max_f32_e32 v42, 0, v42
	v_max_f32_e32 v41, 0, v47
	v_max_f32_e32 v43, 0, v43
	v_pk_mul_f32 v[46:47], v[40:41], v[40:41]
	v_pk_mul_f32 v[54:55], v[42:43], v[42:43]
	v_cvt_pk_bf16_f32 v40, v44, v45
	v_lshl_add_u64 v[44:45], s[88:89], 0, v[48:49]
	v_pk_mul_f32 v[32:33], v[32:33], v[50:51] op_sel_hi:[1,0]
	v_cvt_pk_bf16_f32 v41, v46, v47
	v_cvt_pk_bf16_f32 v42, v52, v53
	v_cvt_pk_bf16_f32 v43, v54, v55
	v_lshl_add_u64 v[44:45], v[44:45], 0, v[120:121]
	v_pk_mul_f32 v[38:39], v[38:39], v[50:51] op_sel_hi:[1,0]
	v_pk_mul_f32 v[36:37], v[36:37], v[50:51] op_sel_hi:[1,0]
	v_pk_mul_f32 v[34:35], v[34:35], v[50:51] op_sel_hi:[1,0]
	v_max_f32_e32 v32, 0, v32
	v_max_f32_e32 v33, 0, v33
	global_store_dwordx4 v[44:45], v[40:43], off
	v_max_f32_e32 v36, 0, v36
	v_max_f32_e32 v37, 0, v37
	v_pk_mul_f32 v[40:41], v[32:33], v[32:33]
	v_max_f32_e32 v32, 0, v38
	v_max_f32_e32 v34, 0, v34
	v_max_f32_e32 v33, 0, v39
	v_max_f32_e32 v35, 0, v35
	v_pk_mul_f32 v[36:37], v[36:37], v[36:37]
	v_pk_mul_f32 v[38:39], v[32:33], v[32:33]
	v_pk_mul_f32 v[42:43], v[34:35], v[34:35]
	v_cvt_pk_bf16_f32 v32, v36, v37
	v_cvt_pk_bf16_f32 v33, v38, v39
	v_cvt_pk_bf16_f32 v34, v40, v41
	v_cvt_pk_bf16_f32 v35, v42, v43
	global_store_dwordx4 v[44:45], v[32:35], off offset:256
	s_nop 1
	v_add_u32_e32 v32, 0xa0, v138
	v_ashrrev_i32_e32 v33, 31, v32
	v_lshlrev_b64 v[32:33], 13, v[32:33]
	v_fmamk_f32 v34, v166, 0x3a800000, v228
	v_cmp_gt_f32_e32 vcc, s69, v34
	v_mul_f32_e32 v35, 0x4b800000, v34
	s_nop 0
	v_cndmask_b32_e32 v34, v34, v35, vcc
	v_rsq_f32_e32 v34, v34
	s_nop 0
	v_mul_f32_e32 v35, 0x45800000, v34
	v_cndmask_b32_e32 v34, v34, v35, vcc
	v_pk_mul_f32 v[28:29], v[28:29], v[34:35] op_sel_hi:[1,0]
	v_pk_mul_f32 v[24:25], v[24:25], v[34:35] op_sel_hi:[1,0]
	v_pk_mul_f32 v[30:31], v[30:31], v[34:35] op_sel_hi:[1,0]
	v_pk_mul_f32 v[26:27], v[26:27], v[34:35] op_sel_hi:[1,0]
	v_max_f32_e32 v28, 0, v28
	v_max_f32_e32 v24, 0, v24
	v_max_f32_e32 v29, 0, v29
	v_max_f32_e32 v25, 0, v25
	v_pk_mul_f32 v[28:29], v[28:29], v[28:29]
	v_pk_mul_f32 v[36:37], v[24:25], v[24:25]
	v_max_f32_e32 v24, 0, v30
	v_max_f32_e32 v26, 0, v26
	v_max_f32_e32 v25, 0, v31
	v_max_f32_e32 v27, 0, v27
	v_pk_mul_f32 v[30:31], v[24:25], v[24:25]
	v_pk_mul_f32 v[38:39], v[26:27], v[26:27]
	v_cvt_pk_bf16_f32 v24, v28, v29
	v_lshl_add_u64 v[28:29], s[88:89], 0, v[32:33]
	v_pk_mul_f32 v[16:17], v[16:17], v[34:35] op_sel_hi:[1,0]
	v_cvt_pk_bf16_f32 v25, v30, v31
	v_cvt_pk_bf16_f32 v26, v36, v37
	v_cvt_pk_bf16_f32 v27, v38, v39
	v_lshl_add_u64 v[28:29], v[28:29], 0, v[120:121]
	v_pk_mul_f32 v[22:23], v[22:23], v[34:35] op_sel_hi:[1,0]
	v_pk_mul_f32 v[20:21], v[20:21], v[34:35] op_sel_hi:[1,0]
	v_pk_mul_f32 v[18:19], v[18:19], v[34:35] op_sel_hi:[1,0]
	v_max_f32_e32 v16, 0, v16
	v_max_f32_e32 v17, 0, v17
	global_store_dwordx4 v[28:29], v[24:27], off
	v_max_f32_e32 v20, 0, v20
	v_max_f32_e32 v21, 0, v21
	v_pk_mul_f32 v[24:25], v[16:17], v[16:17]
	v_max_f32_e32 v16, 0, v22
	v_max_f32_e32 v18, 0, v18
	v_max_f32_e32 v17, 0, v23
	v_max_f32_e32 v19, 0, v19
	v_pk_mul_f32 v[20:21], v[20:21], v[20:21]
	v_pk_mul_f32 v[22:23], v[16:17], v[16:17]
	v_pk_mul_f32 v[26:27], v[18:19], v[18:19]
	v_cvt_pk_bf16_f32 v16, v20, v21
	v_cvt_pk_bf16_f32 v17, v22, v23
	v_cvt_pk_bf16_f32 v18, v24, v25
	v_cvt_pk_bf16_f32 v19, v26, v27
	global_store_dwordx4 v[28:29], v[16:19], off offset:256
	s_nop 1
	v_add_u32_e32 v16, 0xb0, v138
	v_ashrrev_i32_e32 v17, 31, v16
	v_lshlrev_b64 v[16:17], 13, v[16:17]
	v_fmamk_f32 v18, v167, 0x3a800000, v228
	v_cmp_gt_f32_e32 vcc, s69, v18
	v_mul_f32_e32 v19, 0x4b800000, v18
	s_nop 0
	v_cndmask_b32_e32 v18, v18, v19, vcc
	v_rsq_f32_e32 v18, v18
	s_nop 0
	v_mul_f32_e32 v19, 0x45800000, v18
	v_cndmask_b32_e32 v18, v18, v19, vcc
	v_pk_mul_f32 v[12:13], v[12:13], v[18:19] op_sel_hi:[1,0]
	v_pk_mul_f32 v[8:9], v[8:9], v[18:19] op_sel_hi:[1,0]
	v_pk_mul_f32 v[14:15], v[14:15], v[18:19] op_sel_hi:[1,0]
	v_pk_mul_f32 v[10:11], v[10:11], v[18:19] op_sel_hi:[1,0]
	v_max_f32_e32 v12, 0, v12
	v_max_f32_e32 v8, 0, v8
	v_max_f32_e32 v13, 0, v13
	v_max_f32_e32 v9, 0, v9
	v_pk_mul_f32 v[12:13], v[12:13], v[12:13]
	v_pk_mul_f32 v[20:21], v[8:9], v[8:9]
	v_max_f32_e32 v8, 0, v14
	v_max_f32_e32 v10, 0, v10
	v_max_f32_e32 v9, 0, v15
	v_max_f32_e32 v11, 0, v11
	v_pk_mul_f32 v[14:15], v[8:9], v[8:9]
	v_pk_mul_f32 v[22:23], v[10:11], v[10:11]
	v_cvt_pk_bf16_f32 v8, v12, v13
	v_lshl_add_u64 v[12:13], s[88:89], 0, v[16:17]
	v_pk_mul_f32 v[0:1], v[0:1], v[18:19] op_sel_hi:[1,0]
	v_cvt_pk_bf16_f32 v9, v14, v15
	v_cvt_pk_bf16_f32 v10, v20, v21
	v_cvt_pk_bf16_f32 v11, v22, v23
	v_lshl_add_u64 v[12:13], v[12:13], 0, v[120:121]
	v_pk_mul_f32 v[6:7], v[6:7], v[18:19] op_sel_hi:[1,0]
	v_pk_mul_f32 v[4:5], v[4:5], v[18:19] op_sel_hi:[1,0]
	v_pk_mul_f32 v[2:3], v[2:3], v[18:19] op_sel_hi:[1,0]
	v_max_f32_e32 v0, 0, v0
	v_max_f32_e32 v1, 0, v1
	global_store_dwordx4 v[12:13], v[8:11], off
	v_max_f32_e32 v4, 0, v4
	v_max_f32_e32 v5, 0, v5
	v_pk_mul_f32 v[8:9], v[0:1], v[0:1]
	v_max_f32_e32 v0, 0, v6
	v_max_f32_e32 v2, 0, v2
	v_max_f32_e32 v1, 0, v7
	v_max_f32_e32 v3, 0, v3
	v_pk_mul_f32 v[4:5], v[4:5], v[4:5]
	v_pk_mul_f32 v[6:7], v[0:1], v[0:1]
	v_pk_mul_f32 v[10:11], v[2:3], v[2:3]
	v_cvt_pk_bf16_f32 v0, v4, v5
	v_cvt_pk_bf16_f32 v1, v6, v7
	v_cvt_pk_bf16_f32 v2, v8, v9
	v_cvt_pk_bf16_f32 v3, v10, v11
	s_andn2_b64 vcc, exec, s[4:5]
	global_store_dwordx4 v[12:13], v[0:3], off offset:256
	s_cbranch_vccnz .LBB0_787
	s_andn2_b64 vcc, exec, s[0:1]
	s_cbranch_vccnz .LBB0_786
	s_barrier
	s_branch .LBB0_786

.LBB0_869:
	s_add_u32 s10, s24, 0xfff00080
	s_addc_u32 s11, s25, -1
	s_add_i32 s83, 0, 0x10000
	s_cmp_eq_u32 s82, 60
	s_cselect_b32 s29, s19, s11
	s_cselect_b32 s28, s72, s10
	v_add_u32_e32 v142, s83, v145
	s_cselect_b32 s27, s17, s80
	s_cselect_b32 s26, s76, s77
	s_add_i32 s10, 0, 0x14000
	ds_read_b128 v[138:141], v142
	ds_read_b128 v[148:151], v142 offset:1024
	ds_read_b128 v[152:155], v142 offset:2048
	ds_read_b128 v[156:159], v142 offset:3072
	v_add_u32_e32 v142, s10, v145
	ds_read_b128 v[160:163], v142
	ds_read_b128 v[164:167], v142 offset:1024
	ds_read_b128 v[168:171], v142 offset:2048
	ds_read_b128 v[172:175], v142 offset:3072
	v_lshl_add_u64 v[142:143], s[24:25], 0, v[134:135]
	s_add_i32 m0, s34, 0xc000
	ds_read_b128 v[176:179], v147
	ds_read_b128 v[180:183], v147 offset:1024
	ds_read_b128 v[184:187], v147 offset:2048
	ds_read_b128 v[188:191], v147 offset:3072
	ds_read_b128 v[192:195], v147 offset:4096
	ds_read_b128 v[196:199], v147 offset:5120
	ds_read_b128 v[200:203], v147 offset:6144
	ds_read_b128 v[204:207], v147 offset:7168
	global_load_lds_dwordx4 v[142:143], off
	v_lshl_add_u64 v[142:143], s[24:25], 0, v[136:137]
	s_add_i32 m0, s34, 0xe000
	s_nop 0
	global_load_lds_dwordx4 v[142:143], off
	s_waitcnt vmcnt(8)
	s_waitcnt lgkmcnt(0)
	s_barrier
	s_setprio 1
	s_waitcnt lgkmcnt(0)
	v_mfma_f32_16x16x32_bf16 v[124:127], v[138:141], v[176:179], v[124:127]
	v_mfma_f32_16x16x32_bf16 v[120:123], v[152:155], v[176:179], v[120:123]
	v_mfma_f32_16x16x32_bf16 v[108:111], v[138:141], v[184:187], v[108:111]
	v_mfma_f32_16x16x32_bf16 v[104:107], v[152:155], v[184:187], v[104:107]
	v_mfma_f32_16x16x32_bf16 v[92:95], v[138:141], v[192:195], v[92:95]
	v_mfma_f32_16x16x32_bf16 v[88:91], v[152:155], v[192:195], v[88:91]
	v_mfma_f32_16x16x32_bf16 v[76:79], v[138:141], v[200:203], v[76:79]
	v_mfma_f32_16x16x32_bf16 v[72:75], v[152:155], v[200:203], v[72:75]
	v_mfma_f32_16x16x32_bf16 v[124:127], v[148:151], v[180:183], v[124:127]
	v_mfma_f32_16x16x32_bf16 v[120:123], v[156:159], v[180:183], v[120:123]
	v_mfma_f32_16x16x32_bf16 v[108:111], v[148:151], v[188:191], v[108:111]
	v_mfma_f32_16x16x32_bf16 v[104:107], v[156:159], v[188:191], v[104:107]
	v_mfma_f32_16x16x32_bf16 v[92:95], v[148:151], v[196:199], v[92:95]
	v_mfma_f32_16x16x32_bf16 v[88:91], v[156:159], v[196:199], v[88:91]
	v_mfma_f32_16x16x32_bf16 v[76:79], v[148:151], v[204:207], v[76:79]
	v_mfma_f32_16x16x32_bf16 v[72:75], v[156:159], v[204:207], v[72:75]
	s_setprio 0
	s_setprio 1
	v_mfma_f32_16x16x32_bf16 v[116:119], v[160:163], v[176:179], v[116:119]
	v_mfma_f32_16x16x32_bf16 v[112:115], v[168:171], v[176:179], v[112:115]
	v_mfma_f32_16x16x32_bf16 v[100:103], v[160:163], v[184:187], v[100:103]
	v_mfma_f32_16x16x32_bf16 v[96:99], v[168:171], v[184:187], v[96:99]
	v_mfma_f32_16x16x32_bf16 v[84:87], v[160:163], v[192:195], v[84:87]
	v_mfma_f32_16x16x32_bf16 v[80:83], v[168:171], v[192:195], v[80:83]
	v_mfma_f32_16x16x32_bf16 v[68:71], v[160:163], v[200:203], v[68:71]
	v_mfma_f32_16x16x32_bf16 v[64:67], v[168:171], v[200:203], v[64:67]
	v_mfma_f32_16x16x32_bf16 v[116:119], v[164:167], v[180:183], v[116:119]
	v_mfma_f32_16x16x32_bf16 v[112:115], v[172:175], v[180:183], v[112:115]
	v_mfma_f32_16x16x32_bf16 v[100:103], v[164:167], v[188:191], v[100:103]
	v_mfma_f32_16x16x32_bf16 v[96:99], v[172:175], v[188:191], v[96:99]
	v_mfma_f32_16x16x32_bf16 v[84:87], v[164:167], v[196:199], v[84:87]
	v_mfma_f32_16x16x32_bf16 v[80:83], v[172:175], v[196:199], v[80:83]
	v_mfma_f32_16x16x32_bf16 v[68:71], v[164:167], v[204:207], v[68:71]
	v_mfma_f32_16x16x32_bf16 v[64:67], v[172:175], v[204:207], v[64:67]
	s_setprio 0
	s_barrier
	s_add_i32 s11, s83, s31
	v_lshl_add_u64 v[142:143], s[26:27], 0, v[208:209]
	s_mov_b32 m0, s11
	ds_read_b128 v[176:179], v147 offset:16384
	ds_read_b128 v[180:183], v147 offset:17408
	ds_read_b128 v[184:187], v147 offset:18432
	ds_read_b128 v[188:191], v147 offset:19456
	ds_read_b128 v[192:195], v147 offset:20480
	ds_read_b128 v[196:199], v147 offset:21504
	ds_read_b128 v[200:203], v147 offset:22528
	ds_read_b128 v[204:207], v147 offset:23552
	global_load_lds_dwordx4 v[142:143], off
	s_add_i32 m0, s11, 0x2000
	s_add_u32 s96, s26, 0x100000
	v_lshl_add_u64 v[222:223], s[26:27], 0, v[128:129]
	s_addc_u32 s97, s27, 0
	s_add_i32 s10, s10, s31
	global_load_lds_dwordx4 v[222:223], off
	v_lshl_add_u64 v[224:225], s[96:97], 0, v[208:209]
	s_mov_b32 m0, s10
	v_lshl_add_u64 v[236:237], s[28:29], 0, v[130:131]
	global_load_lds_dwordx4 v[224:225], off
	v_lshl_add_u64 v[224:225], s[96:97], 0, v[128:129]
	s_add_i32 m0, s10, 0x2000
	s_nop 0
	global_load_lds_dwordx4 v[224:225], off
	v_lshl_add_u64 v[224:225], s[28:29], 0, v[132:133]
	s_mov_b32 m0, s34
	s_nop 0
	global_load_lds_dwordx4 v[224:225], off
	s_mov_b32 m0, s35
	s_nop 0
	global_load_lds_dwordx4 v[236:237], off
	s_waitcnt vmcnt(8)
	s_waitcnt lgkmcnt(0)
	s_barrier
	s_setprio 1
	s_waitcnt lgkmcnt(0)
	v_mfma_f32_16x16x32_bf16 v[60:63], v[138:141], v[176:179], v[60:63]
	v_mfma_f32_16x16x32_bf16 v[56:59], v[152:155], v[176:179], v[56:59]
	v_mfma_f32_16x16x32_bf16 v[44:47], v[138:141], v[184:187], v[44:47]
	v_mfma_f32_16x16x32_bf16 v[40:43], v[152:155], v[184:187], v[40:43]
	v_mfma_f32_16x16x32_bf16 v[28:31], v[138:141], v[192:195], v[28:31]
	v_mfma_f32_16x16x32_bf16 v[24:27], v[152:155], v[192:195], v[24:27]
	v_mfma_f32_16x16x32_bf16 v[12:15], v[138:141], v[200:203], v[12:15]
	v_mfma_f32_16x16x32_bf16 v[8:11], v[152:155], v[200:203], v[8:11]
	v_mfma_f32_16x16x32_bf16 v[60:63], v[148:151], v[180:183], v[60:63]
	v_mfma_f32_16x16x32_bf16 v[56:59], v[156:159], v[180:183], v[56:59]
	v_mfma_f32_16x16x32_bf16 v[44:47], v[148:151], v[188:191], v[44:47]
	v_mfma_f32_16x16x32_bf16 v[40:43], v[156:159], v[188:191], v[40:43]
	v_mfma_f32_16x16x32_bf16 v[28:31], v[148:151], v[196:199], v[28:31]
	v_mfma_f32_16x16x32_bf16 v[24:27], v[156:159], v[196:199], v[24:27]
	v_mfma_f32_16x16x32_bf16 v[12:15], v[148:151], v[204:207], v[12:15]
	v_mfma_f32_16x16x32_bf16 v[8:11], v[156:159], v[204:207], v[8:11]
	s_setprio 0
	s_setprio 1
	v_mfma_f32_16x16x32_bf16 v[52:55], v[160:163], v[176:179], v[52:55]
	v_mfma_f32_16x16x32_bf16 v[48:51], v[168:171], v[176:179], v[48:51]
	v_mfma_f32_16x16x32_bf16 v[36:39], v[160:163], v[184:187], v[36:39]
	v_mfma_f32_16x16x32_bf16 v[32:35], v[168:171], v[184:187], v[32:35]
	v_mfma_f32_16x16x32_bf16 v[20:23], v[160:163], v[192:195], v[20:23]
	v_mfma_f32_16x16x32_bf16 v[16:19], v[168:171], v[192:195], v[16:19]
	v_mfma_f32_16x16x32_bf16 v[4:7], v[160:163], v[200:203], v[4:7]
	v_mfma_f32_16x16x32_bf16 v[0:3], v[168:171], v[200:203], v[0:3]
	v_mfma_f32_16x16x32_bf16 v[52:55], v[164:167], v[180:183], v[52:55]
	v_mfma_f32_16x16x32_bf16 v[48:51], v[172:175], v[180:183], v[48:51]
	v_mfma_f32_16x16x32_bf16 v[36:39], v[164:167], v[188:191], v[36:39]
	v_mfma_f32_16x16x32_bf16 v[32:35], v[172:175], v[188:191], v[32:35]
	v_mfma_f32_16x16x32_bf16 v[20:23], v[164:167], v[196:199], v[20:23]
	v_mfma_f32_16x16x32_bf16 v[16:19], v[172:175], v[196:199], v[16:19]
	v_mfma_f32_16x16x32_bf16 v[4:7], v[164:167], v[204:207], v[4:7]
	v_mfma_f32_16x16x32_bf16 v[0:3], v[172:175], v[204:207], v[0:3]
	s_setprio 0
	s_barrier
	s_add_i32 s10, 0, 0x18000
	s_add_i32 s11, 0, 0x1c000
	v_add_u32_e32 v156, s10, v145
	v_add_u32_e32 v172, s11, v145
	ds_read_b128 v[138:141], v156
	ds_read_b128 v[148:151], v156 offset:1024
	ds_read_b128 v[152:155], v156 offset:2048
	ds_read_b128 v[156:159], v156 offset:3072
	ds_read_b128 v[160:163], v172
	ds_read_b128 v[164:167], v172 offset:1024
	ds_read_b128 v[168:171], v172 offset:2048
	ds_read_b128 v[172:175], v172 offset:3072
	s_add_u32 s28, s28, 0x100000
	s_addc_u32 s29, s29, 0
	s_mov_b32 m0, s36
	v_lshl_add_u64 v[238:239], s[28:29], 0, v[132:133]
	ds_read_b128 v[176:179], v147 offset:32768
	ds_read_b128 v[180:183], v147 offset:33792
	ds_read_b128 v[184:187], v147 offset:34816
	ds_read_b128 v[188:191], v147 offset:35840
	ds_read_b128 v[192:195], v147 offset:36864
	ds_read_b128 v[196:199], v147 offset:37888
	ds_read_b128 v[200:203], v147 offset:38912
	ds_read_b128 v[204:207], v147 offset:39936
	global_load_lds_dwordx4 v[238:239], off
	v_lshl_add_u64 v[238:239], s[28:29], 0, v[130:131]
	s_mov_b32 m0, s37
	s_nop 0
	global_load_lds_dwordx4 v[238:239], off
	s_waitcnt vmcnt(8)
	s_waitcnt lgkmcnt(0)
	s_barrier
	s_setprio 1
	s_waitcnt lgkmcnt(0)
	v_mfma_f32_16x16x32_bf16 v[124:127], v[138:141], v[176:179], v[124:127]
	v_mfma_f32_16x16x32_bf16 v[120:123], v[152:155], v[176:179], v[120:123]
	v_mfma_f32_16x16x32_bf16 v[108:111], v[138:141], v[184:187], v[108:111]
	v_mfma_f32_16x16x32_bf16 v[104:107], v[152:155], v[184:187], v[104:107]
	v_mfma_f32_16x16x32_bf16 v[92:95], v[138:141], v[192:195], v[92:95]
	v_mfma_f32_16x16x32_bf16 v[88:91], v[152:155], v[192:195], v[88:91]
	v_mfma_f32_16x16x32_bf16 v[76:79], v[138:141], v[200:203], v[76:79]
	v_mfma_f32_16x16x32_bf16 v[72:75], v[152:155], v[200:203], v[72:75]
	v_mfma_f32_16x16x32_bf16 v[124:127], v[148:151], v[180:183], v[124:127]
	v_mfma_f32_16x16x32_bf16 v[120:123], v[156:159], v[180:183], v[120:123]
	v_mfma_f32_16x16x32_bf16 v[108:111], v[148:151], v[188:191], v[108:111]
	v_mfma_f32_16x16x32_bf16 v[104:107], v[156:159], v[188:191], v[104:107]
	v_mfma_f32_16x16x32_bf16 v[92:95], v[148:151], v[196:199], v[92:95]
	v_mfma_f32_16x16x32_bf16 v[88:91], v[156:159], v[196:199], v[88:91]
	v_mfma_f32_16x16x32_bf16 v[76:79], v[148:151], v[204:207], v[76:79]
	v_mfma_f32_16x16x32_bf16 v[72:75], v[156:159], v[204:207], v[72:75]
	s_setprio 0
	s_setprio 1
	v_mfma_f32_16x16x32_bf16 v[116:119], v[160:163], v[176:179], v[116:119]
	v_mfma_f32_16x16x32_bf16 v[112:115], v[168:171], v[176:179], v[112:115]
	v_mfma_f32_16x16x32_bf16 v[100:103], v[160:163], v[184:187], v[100:103]
	v_mfma_f32_16x16x32_bf16 v[96:99], v[168:171], v[184:187], v[96:99]
	v_mfma_f32_16x16x32_bf16 v[84:87], v[160:163], v[192:195], v[84:87]
	v_mfma_f32_16x16x32_bf16 v[80:83], v[168:171], v[192:195], v[80:83]
	v_mfma_f32_16x16x32_bf16 v[68:71], v[160:163], v[200:203], v[68:71]
	v_mfma_f32_16x16x32_bf16 v[64:67], v[168:171], v[200:203], v[64:67]
	v_mfma_f32_16x16x32_bf16 v[116:119], v[164:167], v[180:183], v[116:119]
	v_mfma_f32_16x16x32_bf16 v[112:115], v[172:175], v[180:183], v[112:115]
	v_mfma_f32_16x16x32_bf16 v[100:103], v[164:167], v[188:191], v[100:103]
	v_mfma_f32_16x16x32_bf16 v[96:99], v[172:175], v[188:191], v[96:99]
	v_mfma_f32_16x16x32_bf16 v[84:87], v[164:167], v[196:199], v[84:87]
	v_mfma_f32_16x16x32_bf16 v[80:83], v[172:175], v[196:199], v[80:83]
	v_mfma_f32_16x16x32_bf16 v[68:71], v[164:167], v[204:207], v[68:71]
	v_mfma_f32_16x16x32_bf16 v[64:67], v[172:175], v[204:207], v[64:67]
	s_setprio 0
	s_barrier
	s_add_i32 s10, s10, s31
	v_lshl_add_u64 v[142:143], v[142:143], 0, s[94:95]
	s_mov_b32 m0, s10
	ds_read_b128 v[176:179], v147 offset:49152
	ds_read_b128 v[180:183], v147 offset:50176
	ds_read_b128 v[184:187], v147 offset:51200
	ds_read_b128 v[188:191], v147 offset:52224
	ds_read_b128 v[192:195], v147 offset:53248
	ds_read_b128 v[196:199], v147 offset:54272
	ds_read_b128 v[200:203], v147 offset:55296
	ds_read_b128 v[204:207], v147 offset:56320
	global_load_lds_dwordx4 v[142:143], off
	s_add_i32 m0, s10, 0x2000
	s_add_u32 s26, s26, 0x100080
	v_lshl_add_u64 v[142:143], v[222:223], 0, s[94:95]
	s_addc_u32 s27, s27, 0
	s_add_i32 s10, s11, s31
	global_load_lds_dwordx4 v[142:143], off
	v_lshl_add_u64 v[142:143], s[26:27], 0, v[208:209]
	s_mov_b32 m0, s10
	s_nop 0
	global_load_lds_dwordx4 v[142:143], off
	v_lshl_add_u64 v[142:143], s[26:27], 0, v[128:129]
	s_add_i32 m0, s10, 0x2000
	s_nop 0
	global_load_lds_dwordx4 v[142:143], off
	v_lshl_add_u64 v[142:143], v[224:225], 0, s[94:95]
	s_mov_b32 m0, s40
	s_nop 0
	global_load_lds_dwordx4 v[142:143], off
	v_lshl_add_u64 v[142:143], v[236:237], 0, s[94:95]
	s_mov_b32 m0, s41
	s_nop 0
	global_load_lds_dwordx4 v[142:143], off
	s_waitcnt vmcnt(8)
	s_waitcnt lgkmcnt(0)
	s_barrier
	s_setprio 1
	s_waitcnt lgkmcnt(0)
	v_mfma_f32_16x16x32_bf16 v[60:63], v[138:141], v[176:179], v[60:63]
	v_mfma_f32_16x16x32_bf16 v[56:59], v[152:155], v[176:179], v[56:59]
	v_mfma_f32_16x16x32_bf16 v[44:47], v[138:141], v[184:187], v[44:47]
	v_mfma_f32_16x16x32_bf16 v[40:43], v[152:155], v[184:187], v[40:43]
	v_mfma_f32_16x16x32_bf16 v[28:31], v[138:141], v[192:195], v[28:31]
	v_mfma_f32_16x16x32_bf16 v[24:27], v[152:155], v[192:195], v[24:27]
	v_mfma_f32_16x16x32_bf16 v[12:15], v[138:141], v[200:203], v[12:15]
	v_mfma_f32_16x16x32_bf16 v[8:11], v[152:155], v[200:203], v[8:11]
	v_mfma_f32_16x16x32_bf16 v[60:63], v[148:151], v[180:183], v[60:63]
	v_mfma_f32_16x16x32_bf16 v[56:59], v[156:159], v[180:183], v[56:59]
	v_mfma_f32_16x16x32_bf16 v[44:47], v[148:151], v[188:191], v[44:47]
	v_mfma_f32_16x16x32_bf16 v[40:43], v[156:159], v[188:191], v[40:43]
	v_mfma_f32_16x16x32_bf16 v[28:31], v[148:151], v[196:199], v[28:31]
	v_mfma_f32_16x16x32_bf16 v[24:27], v[156:159], v[196:199], v[24:27]
	v_mfma_f32_16x16x32_bf16 v[12:15], v[148:151], v[204:207], v[12:15]
	v_mfma_f32_16x16x32_bf16 v[8:11], v[156:159], v[204:207], v[8:11]
	s_setprio 0
	s_setprio 1
	v_mfma_f32_16x16x32_bf16 v[52:55], v[160:163], v[176:179], v[52:55]
	v_mfma_f32_16x16x32_bf16 v[48:51], v[168:171], v[176:179], v[48:51]
	v_mfma_f32_16x16x32_bf16 v[36:39], v[160:163], v[184:187], v[36:39]
	v_mfma_f32_16x16x32_bf16 v[32:35], v[168:171], v[184:187], v[32:35]
	v_mfma_f32_16x16x32_bf16 v[20:23], v[160:163], v[192:195], v[20:23]
	v_mfma_f32_16x16x32_bf16 v[16:19], v[168:171], v[192:195], v[16:19]
	v_mfma_f32_16x16x32_bf16 v[4:7], v[160:163], v[200:203], v[4:7]
	v_mfma_f32_16x16x32_bf16 v[0:3], v[168:171], v[200:203], v[0:3]
	v_mfma_f32_16x16x32_bf16 v[52:55], v[164:167], v[180:183], v[52:55]
	v_mfma_f32_16x16x32_bf16 v[48:51], v[172:175], v[180:183], v[48:51]
	v_mfma_f32_16x16x32_bf16 v[36:39], v[164:167], v[188:191], v[36:39]
	v_mfma_f32_16x16x32_bf16 v[32:35], v[172:175], v[188:191], v[32:35]
	v_mfma_f32_16x16x32_bf16 v[20:23], v[164:167], v[196:199], v[20:23]
	v_mfma_f32_16x16x32_bf16 v[16:19], v[172:175], v[196:199], v[16:19]
	v_mfma_f32_16x16x32_bf16 v[4:7], v[164:167], v[204:207], v[4:7]
	v_mfma_f32_16x16x32_bf16 v[0:3], v[172:175], v[204:207], v[0:3]
	s_setprio 0
	s_barrier
	s_add_i32 s82, s82, 2
	s_add_u32 s24, s24, 0x100
	s_addc_u32 s25, s25, 0
	s_add_u32 s77, s77, 0x100
	s_addc_u32 s80, s80, 0
	s_cmp_gt_u32 s82, 61
	s_cbranch_scc0 .LBB0_869
	v_lshl_add_u32 v140, s70, 8, v144
	v_lshl_or_b32 v138, s43, 8, v146
	v_lshlrev_b32_e32 v139, 2, v140
	v_lshlrev_b32_e32 v140, 11, v140
	v_lshl_add_u32 v138, v138, 1, v140
	s_mov_b64 s[100:101], s[46:47]
	global_load_dwordx4 v[148:151], v138, s[100:101]
	global_load_dwordx4 v[152:155], v138, s[100:101] offset:256
	s_add_u32 s100, s100, 0x8000
	s_addc_u32 s101, s101, 0
	global_load_dwordx4 v[156:159], v138, s[100:101]
	global_load_dwordx4 v[160:163], v138, s[100:101] offset:256
	s_add_u32 s100, s100, 0x8000
	s_addc_u32 s101, s101, 0
	global_load_dwordx4 v[164:167], v138, s[100:101]
	global_load_dwordx4 v[168:171], v138, s[100:101] offset:256
	s_add_u32 s100, s100, 0x8000
	s_addc_u32 s101, s101, 0
	global_load_dwordx4 v[172:175], v138, s[100:101]
	global_load_dwordx4 v[176:179], v138, s[100:101] offset:256
	s_add_u32 s100, s100, 0x28000
	s_addc_u32 s101, s101, 0
	global_load_dwordx4 v[180:183], v138, s[100:101]
	global_load_dwordx4 v[184:187], v138, s[100:101] offset:256
	s_add_u32 s100, s100, 0x8000
	s_addc_u32 s101, s101, 0
	global_load_dwordx4 v[188:191], v138, s[100:101]
	global_load_dwordx4 v[192:195], v138, s[100:101] offset:256
	s_add_u32 s100, s100, 0x8000
	s_addc_u32 s101, s101, 0
	global_load_dwordx4 v[196:199], v138, s[100:101]
	global_load_dwordx4 v[200:203], v138, s[100:101] offset:256
	s_add_u32 s100, s100, 0x8000
	s_addc_u32 s101, s101, 0
	global_load_dwordx4 v[204:207], v138, s[100:101]
	global_load_dwordx4 v[236:239], v138, s[100:101] offset:256
	s_and_b64 vcc, exec, s[14:15]
	s_cbranch_vccz .LBB0_872
	s_barrier
.LBB0_872:
	v_xor_b32_e32 v140, 16, v230
	v_xor_b32_e32 v141, 32, v230
	v_lshlrev_b32_e32 v140, 2, v140
	v_lshlrev_b32_e32 v141, 2, v141
	s_mov_b64 s[100:101], s[46:47]
	s_waitcnt vmcnt(14)
	v_lshlrev_b32_e32 v142, 16, v148
	v_and_b32_e32 v143, 0xffff0000, v148
	v_pk_add_f32 v[124:125], v[124:125], v[142:143]
	v_pk_mul_f32 v[222:223], v[124:125], v[124:125]
	v_cvt_pk_bf16_f32 v148, v124, v125
	v_lshlrev_b32_e32 v142, 16, v149
	v_and_b32_e32 v143, 0xffff0000, v149
	v_pk_add_f32 v[126:127], v[126:127], v[142:143]
	v_pk_fma_f32 v[222:223], v[126:127], v[126:127], v[222:223]
	v_cvt_pk_bf16_f32 v149, v126, v127
	v_lshlrev_b32_e32 v142, 16, v150
	v_and_b32_e32 v143, 0xffff0000, v150
	v_pk_add_f32 v[120:121], v[120:121], v[142:143]
	v_pk_fma_f32 v[222:223], v[120:121], v[120:121], v[222:223]
	v_cvt_pk_bf16_f32 v150, v120, v121
	v_lshlrev_b32_e32 v142, 16, v151
	v_and_b32_e32 v143, 0xffff0000, v151
	v_pk_add_f32 v[122:123], v[122:123], v[142:143]
	v_pk_fma_f32 v[222:223], v[122:123], v[122:123], v[222:223]
	v_cvt_pk_bf16_f32 v151, v122, v123
	global_store_dwordx4 v138, v[148:151], s[100:101]
	v_lshlrev_b32_e32 v142, 16, v152
	v_and_b32_e32 v143, 0xffff0000, v152
	v_pk_add_f32 v[116:117], v[116:117], v[142:143]
	v_pk_fma_f32 v[222:223], v[116:117], v[116:117], v[222:223]
	v_cvt_pk_bf16_f32 v152, v116, v117
	v_lshlrev_b32_e32 v142, 16, v153
	v_and_b32_e32 v143, 0xffff0000, v153
	v_pk_add_f32 v[118:119], v[118:119], v[142:143]
	v_pk_fma_f32 v[222:223], v[118:119], v[118:119], v[222:223]
	v_cvt_pk_bf16_f32 v153, v118, v119
	v_lshlrev_b32_e32 v142, 16, v154
	v_and_b32_e32 v143, 0xffff0000, v154
	v_pk_add_f32 v[112:113], v[112:113], v[142:143]
	v_pk_fma_f32 v[222:223], v[112:113], v[112:113], v[222:223]
	v_cvt_pk_bf16_f32 v154, v112, v113
	v_lshlrev_b32_e32 v142, 16, v155
	v_and_b32_e32 v143, 0xffff0000, v155
	v_pk_add_f32 v[114:115], v[114:115], v[142:143]
	v_pk_fma_f32 v[222:223], v[114:115], v[114:115], v[222:223]
	v_cvt_pk_bf16_f32 v155, v114, v115
	global_store_dwordx4 v138, v[152:155], s[100:101] offset:256
	v_add_f32_e32 v124, v222, v223
	s_add_u32 s100, s100, 0x8000
	s_addc_u32 s101, s101, 0
	s_waitcnt vmcnt(14)
	v_lshlrev_b32_e32 v142, 16, v156
	v_and_b32_e32 v143, 0xffff0000, v156
	v_pk_add_f32 v[108:109], v[108:109], v[142:143]
	v_pk_mul_f32 v[222:223], v[108:109], v[108:109]
	v_cvt_pk_bf16_f32 v156, v108, v109
	v_lshlrev_b32_e32 v142, 16, v157
	v_and_b32_e32 v143, 0xffff0000, v157
	v_pk_add_f32 v[110:111], v[110:111], v[142:143]
	v_pk_fma_f32 v[222:223], v[110:111], v[110:111], v[222:223]
	v_cvt_pk_bf16_f32 v157, v110, v111
	v_lshlrev_b32_e32 v142, 16, v158
	v_and_b32_e32 v143, 0xffff0000, v158
	v_pk_add_f32 v[104:105], v[104:105], v[142:143]
	v_pk_fma_f32 v[222:223], v[104:105], v[104:105], v[222:223]
	v_cvt_pk_bf16_f32 v158, v104, v105
	v_lshlrev_b32_e32 v142, 16, v159
	v_and_b32_e32 v143, 0xffff0000, v159
	v_pk_add_f32 v[106:107], v[106:107], v[142:143]
	v_pk_fma_f32 v[222:223], v[106:107], v[106:107], v[222:223]
	v_cvt_pk_bf16_f32 v159, v106, v107
	global_store_dwordx4 v138, v[156:159], s[100:101]
	v_lshlrev_b32_e32 v142, 16, v160
	v_and_b32_e32 v143, 0xffff0000, v160
	v_pk_add_f32 v[100:101], v[100:101], v[142:143]
	v_pk_fma_f32 v[222:223], v[100:101], v[100:101], v[222:223]
	v_cvt_pk_bf16_f32 v160, v100, v101
	v_lshlrev_b32_e32 v142, 16, v161
	v_and_b32_e32 v143, 0xffff0000, v161
	v_pk_add_f32 v[102:103], v[102:103], v[142:143]
	v_pk_fma_f32 v[222:223], v[102:103], v[102:103], v[222:223]
	v_cvt_pk_bf16_f32 v161, v102, v103
	v_lshlrev_b32_e32 v142, 16, v162
	v_and_b32_e32 v143, 0xffff0000, v162
	v_pk_add_f32 v[96:97], v[96:97], v[142:143]
	v_pk_fma_f32 v[222:223], v[96:97], v[96:97], v[222:223]
	v_cvt_pk_bf16_f32 v162, v96, v97
	v_lshlrev_b32_e32 v142, 16, v163
	v_and_b32_e32 v143, 0xffff0000, v163
	v_pk_add_f32 v[98:99], v[98:99], v[142:143]
	v_pk_fma_f32 v[222:223], v[98:99], v[98:99], v[222:223]
	v_cvt_pk_bf16_f32 v163, v98, v99
	global_store_dwordx4 v138, v[160:163], s[100:101] offset:256
	v_add_f32_e32 v108, v222, v223
	s_add_u32 s100, s100, 0x8000
	s_addc_u32 s101, s101, 0
	s_waitcnt vmcnt(14)
	v_lshlrev_b32_e32 v142, 16, v164
	v_and_b32_e32 v143, 0xffff0000, v164
	v_pk_add_f32 v[92:93], v[92:93], v[142:143]
	v_pk_mul_f32 v[222:223], v[92:93], v[92:93]
	v_cvt_pk_bf16_f32 v164, v92, v93
	v_lshlrev_b32_e32 v142, 16, v165
	v_and_b32_e32 v143, 0xffff0000, v165
	v_pk_add_f32 v[94:95], v[94:95], v[142:143]
	v_pk_fma_f32 v[222:223], v[94:95], v[94:95], v[222:223]
	v_cvt_pk_bf16_f32 v165, v94, v95
	v_lshlrev_b32_e32 v142, 16, v166
	v_and_b32_e32 v143, 0xffff0000, v166
	v_pk_add_f32 v[88:89], v[88:89], v[142:143]
	v_pk_fma_f32 v[222:223], v[88:89], v[88:89], v[222:223]
	v_cvt_pk_bf16_f32 v166, v88, v89
	v_lshlrev_b32_e32 v142, 16, v167
	v_and_b32_e32 v143, 0xffff0000, v167
	v_pk_add_f32 v[90:91], v[90:91], v[142:143]
	v_pk_fma_f32 v[222:223], v[90:91], v[90:91], v[222:223]
	v_cvt_pk_bf16_f32 v167, v90, v91
	global_store_dwordx4 v138, v[164:167], s[100:101]
	v_lshlrev_b32_e32 v142, 16, v168
	v_and_b32_e32 v143, 0xffff0000, v168
	v_pk_add_f32 v[84:85], v[84:85], v[142:143]
	v_pk_fma_f32 v[222:223], v[84:85], v[84:85], v[222:223]
	v_cvt_pk_bf16_f32 v168, v84, v85
	v_lshlrev_b32_e32 v142, 16, v169
	v_and_b32_e32 v143, 0xffff0000, v169
	v_pk_add_f32 v[86:87], v[86:87], v[142:143]
	v_pk_fma_f32 v[222:223], v[86:87], v[86:87], v[222:223]
	v_cvt_pk_bf16_f32 v169, v86, v87
	v_lshlrev_b32_e32 v142, 16, v170
	v_and_b32_e32 v143, 0xffff0000, v170
	v_pk_add_f32 v[80:81], v[80:81], v[142:143]
	v_pk_fma_f32 v[222:223], v[80:81], v[80:81], v[222:223]
	v_cvt_pk_bf16_f32 v170, v80, v81
	v_lshlrev_b32_e32 v142, 16, v171
	v_and_b32_e32 v143, 0xffff0000, v171
	v_pk_add_f32 v[82:83], v[82:83], v[142:143]
	v_pk_fma_f32 v[222:223], v[82:83], v[82:83], v[222:223]
	v_cvt_pk_bf16_f32 v171, v82, v83
	global_store_dwordx4 v138, v[168:171], s[100:101] offset:256
	v_add_f32_e32 v92, v222, v223
	s_add_u32 s100, s100, 0x8000
	s_addc_u32 s101, s101, 0
	s_waitcnt vmcnt(14)
	v_lshlrev_b32_e32 v142, 16, v172
	v_and_b32_e32 v143, 0xffff0000, v172
	v_pk_add_f32 v[76:77], v[76:77], v[142:143]
	v_pk_mul_f32 v[222:223], v[76:77], v[76:77]
	v_cvt_pk_bf16_f32 v172, v76, v77
	v_lshlrev_b32_e32 v142, 16, v173
	v_and_b32_e32 v143, 0xffff0000, v173
	v_pk_add_f32 v[78:79], v[78:79], v[142:143]
	v_pk_fma_f32 v[222:223], v[78:79], v[78:79], v[222:223]
	v_cvt_pk_bf16_f32 v173, v78, v79
	v_lshlrev_b32_e32 v142, 16, v174
	v_and_b32_e32 v143, 0xffff0000, v174
	v_pk_add_f32 v[72:73], v[72:73], v[142:143]
	v_pk_fma_f32 v[222:223], v[72:73], v[72:73], v[222:223]
	v_cvt_pk_bf16_f32 v174, v72, v73
	v_lshlrev_b32_e32 v142, 16, v175
	v_and_b32_e32 v143, 0xffff0000, v175
	v_pk_add_f32 v[74:75], v[74:75], v[142:143]
	v_pk_fma_f32 v[222:223], v[74:75], v[74:75], v[222:223]
	v_cvt_pk_bf16_f32 v175, v74, v75
	global_store_dwordx4 v138, v[172:175], s[100:101]
	v_lshlrev_b32_e32 v142, 16, v176
	v_and_b32_e32 v143, 0xffff0000, v176
	v_pk_add_f32 v[68:69], v[68:69], v[142:143]
	v_pk_fma_f32 v[222:223], v[68:69], v[68:69], v[222:223]
	v_cvt_pk_bf16_f32 v176, v68, v69
	v_lshlrev_b32_e32 v142, 16, v177
	v_and_b32_e32 v143, 0xffff0000, v177
	v_pk_add_f32 v[70:71], v[70:71], v[142:143]
	v_pk_fma_f32 v[222:223], v[70:71], v[70:71], v[222:223]
	v_cvt_pk_bf16_f32 v177, v70, v71
	v_lshlrev_b32_e32 v142, 16, v178
	v_and_b32_e32 v143, 0xffff0000, v178
	v_pk_add_f32 v[64:65], v[64:65], v[142:143]
	v_pk_fma_f32 v[222:223], v[64:65], v[64:65], v[222:223]
	v_cvt_pk_bf16_f32 v178, v64, v65
	v_lshlrev_b32_e32 v142, 16, v179
	v_and_b32_e32 v143, 0xffff0000, v179
	v_pk_add_f32 v[66:67], v[66:67], v[142:143]
	v_pk_fma_f32 v[222:223], v[66:67], v[66:67], v[222:223]
	v_cvt_pk_bf16_f32 v179, v66, v67
	global_store_dwordx4 v138, v[176:179], s[100:101] offset:256
	v_add_f32_e32 v76, v222, v223
	s_add_u32 s100, s100, 0x28000
	s_addc_u32 s101, s101, 0
	s_waitcnt vmcnt(14)
	v_lshlrev_b32_e32 v142, 16, v180
	v_and_b32_e32 v143, 0xffff0000, v180
	v_pk_add_f32 v[60:61], v[60:61], v[142:143]
	v_pk_mul_f32 v[222:223], v[60:61], v[60:61]
	v_cvt_pk_bf16_f32 v180, v60, v61
	v_lshlrev_b32_e32 v142, 16, v181
	v_and_b32_e32 v143, 0xffff0000, v181
	v_pk_add_f32 v[62:63], v[62:63], v[142:143]
	v_pk_fma_f32 v[222:223], v[62:63], v[62:63], v[222:223]
	v_cvt_pk_bf16_f32 v181, v62, v63
	v_lshlrev_b32_e32 v142, 16, v182
	v_and_b32_e32 v143, 0xffff0000, v182
	v_pk_add_f32 v[56:57], v[56:57], v[142:143]
	v_pk_fma_f32 v[222:223], v[56:57], v[56:57], v[222:223]
	v_cvt_pk_bf16_f32 v182, v56, v57
	v_lshlrev_b32_e32 v142, 16, v183
	v_and_b32_e32 v143, 0xffff0000, v183
	v_pk_add_f32 v[58:59], v[58:59], v[142:143]
	v_pk_fma_f32 v[222:223], v[58:59], v[58:59], v[222:223]
	v_cvt_pk_bf16_f32 v183, v58, v59
	global_store_dwordx4 v138, v[180:183], s[100:101]
	v_lshlrev_b32_e32 v142, 16, v184
	v_and_b32_e32 v143, 0xffff0000, v184
	v_pk_add_f32 v[52:53], v[52:53], v[142:143]
	v_pk_fma_f32 v[222:223], v[52:53], v[52:53], v[222:223]
	v_cvt_pk_bf16_f32 v184, v52, v53
	v_lshlrev_b32_e32 v142, 16, v185
	v_and_b32_e32 v143, 0xffff0000, v185
	v_pk_add_f32 v[54:55], v[54:55], v[142:143]
	v_pk_fma_f32 v[222:223], v[54:55], v[54:55], v[222:223]
	v_cvt_pk_bf16_f32 v185, v54, v55
	v_lshlrev_b32_e32 v142, 16, v186
	v_and_b32_e32 v143, 0xffff0000, v186
	v_pk_add_f32 v[48:49], v[48:49], v[142:143]
	v_pk_fma_f32 v[222:223], v[48:49], v[48:49], v[222:223]
	v_cvt_pk_bf16_f32 v186, v48, v49
	v_lshlrev_b32_e32 v142, 16, v187
	v_and_b32_e32 v143, 0xffff0000, v187
	v_pk_add_f32 v[50:51], v[50:51], v[142:143]
	v_pk_fma_f32 v[222:223], v[50:51], v[50:51], v[222:223]
	v_cvt_pk_bf16_f32 v187, v50, v51
	global_store_dwordx4 v138, v[184:187], s[100:101] offset:256
	v_add_f32_e32 v60, v222, v223
	s_add_u32 s100, s100, 0x8000
	s_addc_u32 s101, s101, 0
	s_waitcnt vmcnt(14)
	v_lshlrev_b32_e32 v142, 16, v188
	v_and_b32_e32 v143, 0xffff0000, v188
	v_pk_add_f32 v[44:45], v[44:45], v[142:143]
	v_pk_mul_f32 v[222:223], v[44:45], v[44:45]
	v_cvt_pk_bf16_f32 v188, v44, v45
	v_lshlrev_b32_e32 v142, 16, v189
	v_and_b32_e32 v143, 0xffff0000, v189
	v_pk_add_f32 v[46:47], v[46:47], v[142:143]
	v_pk_fma_f32 v[222:223], v[46:47], v[46:47], v[222:223]
	v_cvt_pk_bf16_f32 v189, v46, v47
	v_lshlrev_b32_e32 v142, 16, v190
	v_and_b32_e32 v143, 0xffff0000, v190
	v_pk_add_f32 v[40:41], v[40:41], v[142:143]
	v_pk_fma_f32 v[222:223], v[40:41], v[40:41], v[222:223]
	v_cvt_pk_bf16_f32 v190, v40, v41
	v_lshlrev_b32_e32 v142, 16, v191
	v_and_b32_e32 v143, 0xffff0000, v191
	v_pk_add_f32 v[42:43], v[42:43], v[142:143]
	v_pk_fma_f32 v[222:223], v[42:43], v[42:43], v[222:223]
	v_cvt_pk_bf16_f32 v191, v42, v43
	global_store_dwordx4 v138, v[188:191], s[100:101]
	v_lshlrev_b32_e32 v142, 16, v192
	v_and_b32_e32 v143, 0xffff0000, v192
	v_pk_add_f32 v[36:37], v[36:37], v[142:143]
	v_pk_fma_f32 v[222:223], v[36:37], v[36:37], v[222:223]
	v_cvt_pk_bf16_f32 v192, v36, v37
	v_lshlrev_b32_e32 v142, 16, v193
	v_and_b32_e32 v143, 0xffff0000, v193
	v_pk_add_f32 v[38:39], v[38:39], v[142:143]
	v_pk_fma_f32 v[222:223], v[38:39], v[38:39], v[222:223]
	v_cvt_pk_bf16_f32 v193, v38, v39
	v_lshlrev_b32_e32 v142, 16, v194
	v_and_b32_e32 v143, 0xffff0000, v194
	v_pk_add_f32 v[32:33], v[32:33], v[142:143]
	v_pk_fma_f32 v[222:223], v[32:33], v[32:33], v[222:223]
	v_cvt_pk_bf16_f32 v194, v32, v33
	v_lshlrev_b32_e32 v142, 16, v195
	v_and_b32_e32 v143, 0xffff0000, v195
	v_pk_add_f32 v[34:35], v[34:35], v[142:143]
	v_pk_fma_f32 v[222:223], v[34:35], v[34:35], v[222:223]
	v_cvt_pk_bf16_f32 v195, v34, v35
	global_store_dwordx4 v138, v[192:195], s[100:101] offset:256
	v_add_f32_e32 v44, v222, v223
	s_add_u32 s100, s100, 0x8000
	s_addc_u32 s101, s101, 0
	s_waitcnt vmcnt(14)
	v_lshlrev_b32_e32 v142, 16, v196
	v_and_b32_e32 v143, 0xffff0000, v196
	v_pk_add_f32 v[28:29], v[28:29], v[142:143]
	v_pk_mul_f32 v[222:223], v[28:29], v[28:29]
	v_cvt_pk_bf16_f32 v196, v28, v29
	v_lshlrev_b32_e32 v142, 16, v197
	v_and_b32_e32 v143, 0xffff0000, v197
	v_pk_add_f32 v[30:31], v[30:31], v[142:143]
	v_pk_fma_f32 v[222:223], v[30:31], v[30:31], v[222:223]
	v_cvt_pk_bf16_f32 v197, v30, v31
	v_lshlrev_b32_e32 v142, 16, v198
	v_and_b32_e32 v143, 0xffff0000, v198
	v_pk_add_f32 v[24:25], v[24:25], v[142:143]
	v_pk_fma_f32 v[222:223], v[24:25], v[24:25], v[222:223]
	v_cvt_pk_bf16_f32 v198, v24, v25
	v_lshlrev_b32_e32 v142, 16, v199
	v_and_b32_e32 v143, 0xffff0000, v199
	v_pk_add_f32 v[26:27], v[26:27], v[142:143]
	v_pk_fma_f32 v[222:223], v[26:27], v[26:27], v[222:223]
	v_cvt_pk_bf16_f32 v199, v26, v27
	global_store_dwordx4 v138, v[196:199], s[100:101]
	v_lshlrev_b32_e32 v142, 16, v200
	v_and_b32_e32 v143, 0xffff0000, v200
	v_pk_add_f32 v[20:21], v[20:21], v[142:143]
	v_pk_fma_f32 v[222:223], v[20:21], v[20:21], v[222:223]
	v_cvt_pk_bf16_f32 v200, v20, v21
	v_lshlrev_b32_e32 v142, 16, v201
	v_and_b32_e32 v143, 0xffff0000, v201
	v_pk_add_f32 v[22:23], v[22:23], v[142:143]
	v_pk_fma_f32 v[222:223], v[22:23], v[22:23], v[222:223]
	v_cvt_pk_bf16_f32 v201, v22, v23
	v_lshlrev_b32_e32 v142, 16, v202
	v_and_b32_e32 v143, 0xffff0000, v202
	v_pk_add_f32 v[16:17], v[16:17], v[142:143]
	v_pk_fma_f32 v[222:223], v[16:17], v[16:17], v[222:223]
	v_cvt_pk_bf16_f32 v202, v16, v17
	v_lshlrev_b32_e32 v142, 16, v203
	v_and_b32_e32 v143, 0xffff0000, v203
	v_pk_add_f32 v[18:19], v[18:19], v[142:143]
	v_pk_fma_f32 v[222:223], v[18:19], v[18:19], v[222:223]
	v_cvt_pk_bf16_f32 v203, v18, v19
	global_store_dwordx4 v138, v[200:203], s[100:101] offset:256
	v_add_f32_e32 v28, v222, v223
	s_add_u32 s100, s100, 0x8000
	s_addc_u32 s101, s101, 0
	s_waitcnt vmcnt(14)
	v_lshlrev_b32_e32 v142, 16, v204
	v_and_b32_e32 v143, 0xffff0000, v204
	v_pk_add_f32 v[12:13], v[12:13], v[142:143]
	v_pk_mul_f32 v[222:223], v[12:13], v[12:13]
	v_cvt_pk_bf16_f32 v204, v12, v13
	v_lshlrev_b32_e32 v142, 16, v205
	v_and_b32_e32 v143, 0xffff0000, v205
	v_pk_add_f32 v[14:15], v[14:15], v[142:143]
	v_pk_fma_f32 v[222:223], v[14:15], v[14:15], v[222:223]
	v_cvt_pk_bf16_f32 v205, v14, v15
	v_lshlrev_b32_e32 v142, 16, v206
	v_and_b32_e32 v143, 0xffff0000, v206
	v_pk_add_f32 v[8:9], v[8:9], v[142:143]
	v_pk_fma_f32 v[222:223], v[8:9], v[8:9], v[222:223]
	v_cvt_pk_bf16_f32 v206, v8, v9
	v_lshlrev_b32_e32 v142, 16, v207
	v_and_b32_e32 v143, 0xffff0000, v207
	v_pk_add_f32 v[10:11], v[10:11], v[142:143]
	v_pk_fma_f32 v[222:223], v[10:11], v[10:11], v[222:223]
	v_cvt_pk_bf16_f32 v207, v10, v11
	global_store_dwordx4 v138, v[204:207], s[100:101]
	v_lshlrev_b32_e32 v142, 16, v236
	v_and_b32_e32 v143, 0xffff0000, v236
	v_pk_add_f32 v[4:5], v[4:5], v[142:143]
	v_pk_fma_f32 v[222:223], v[4:5], v[4:5], v[222:223]
	v_cvt_pk_bf16_f32 v236, v4, v5
	v_lshlrev_b32_e32 v142, 16, v237
	v_and_b32_e32 v143, 0xffff0000, v237
	v_pk_add_f32 v[6:7], v[6:7], v[142:143]
	v_pk_fma_f32 v[222:223], v[6:7], v[6:7], v[222:223]
	v_cvt_pk_bf16_f32 v237, v6, v7
	v_lshlrev_b32_e32 v142, 16, v238
	v_and_b32_e32 v143, 0xffff0000, v238
	v_pk_add_f32 v[0:1], v[0:1], v[142:143]
	v_pk_fma_f32 v[222:223], v[0:1], v[0:1], v[222:223]
	v_cvt_pk_bf16_f32 v238, v0, v1
	v_lshlrev_b32_e32 v142, 16, v239
	v_and_b32_e32 v143, 0xffff0000, v239
	v_pk_add_f32 v[2:3], v[2:3], v[142:143]
	v_pk_fma_f32 v[222:223], v[2:3], v[2:3], v[222:223]
	v_cvt_pk_bf16_f32 v239, v2, v3
	global_store_dwordx4 v138, v[236:239], s[100:101] offset:256
	v_add_f32_e32 v12, v222, v223
	ds_bpermute_b32 v125, v140, v124
	ds_bpermute_b32 v109, v140, v108
	ds_bpermute_b32 v93, v140, v92
	ds_bpermute_b32 v77, v140, v76
	ds_bpermute_b32 v61, v140, v60
	ds_bpermute_b32 v45, v140, v44
	ds_bpermute_b32 v29, v140, v28
	ds_bpermute_b32 v13, v140, v12
	s_waitcnt lgkmcnt(0)
	v_add_f32_e32 v124, v124, v125
	v_add_f32_e32 v108, v108, v109
	v_add_f32_e32 v92, v92, v93
	v_add_f32_e32 v76, v76, v77
	v_add_f32_e32 v60, v60, v61
	v_add_f32_e32 v44, v44, v45
	v_add_f32_e32 v28, v28, v29
	v_add_f32_e32 v12, v12, v13
	ds_bpermute_b32 v125, v141, v124
	ds_bpermute_b32 v109, v141, v108
	ds_bpermute_b32 v93, v141, v92
	ds_bpermute_b32 v77, v141, v76
	ds_bpermute_b32 v61, v141, v60
	ds_bpermute_b32 v45, v141, v44
	ds_bpermute_b32 v29, v141, v28
	ds_bpermute_b32 v13, v141, v12
	s_waitcnt lgkmcnt(0)
	v_add_f32_e32 v124, v124, v125
	v_add_f32_e32 v108, v108, v109
	v_add_f32_e32 v92, v92, v93
	v_add_f32_e32 v76, v76, v77
	v_add_f32_e32 v60, v60, v61
	v_add_f32_e32 v44, v44, v45
	v_add_f32_e32 v28, v28, v29
	v_add_f32_e32 v12, v12, v13
	s_and_saveexec_b64 s[98:99], s[4:5]
	global_atomic_add_f32 v139, v124, s[12:13]
	global_atomic_add_f32 v139, v108, s[12:13] offset:64
	global_atomic_add_f32 v139, v92, s[12:13] offset:128
	global_atomic_add_f32 v139, v76, s[12:13] offset:192
	global_atomic_add_f32 v139, v60, s[12:13] offset:512
	global_atomic_add_f32 v139, v44, s[12:13] offset:576
	global_atomic_add_f32 v139, v28, s[12:13] offset:640
	global_atomic_add_f32 v139, v12, s[12:13] offset:704
	s_or_b64 exec, exec, s[98:99]
	v_readlane_b32 s76, v252, 46
	s_mov_b32 s77, 0x20000
	s_mov_b32 s28, 0x30000
	s_mov_b32 s29, 0x40000
	s_mov_b32 s72, 0x50000
	s_andn2_b64 vcc, exec, s[6:7]
	s_mov_b64 s[6:7], -1
	s_cbranch_vccnz .LBB0_861
	s_andn2_b64 vcc, exec, s[0:1]
	s_cbranch_vccnz .LBB0_860
	s_barrier
	s_branch .LBB0_860

	.amdhsa_kernel _Z8mega_fwd4Args
		.amdhsa_group_segment_fixed_size 0
		.amdhsa_private_segment_fixed_size 0
		.amdhsa_kernarg_size 400
		.amdhsa_user_sgpr_count 2
		.amdhsa_user_sgpr_dispatch_ptr 0
		.amdhsa_user_sgpr_queue_ptr 0
		.amdhsa_user_sgpr_kernarg_segment_ptr 1
		.amdhsa_user_sgpr_dispatch_id 0
		.amdhsa_user_sgpr_kernarg_preload_length 0
		.amdhsa_user_sgpr_kernarg_preload_offset 0
		.amdhsa_user_sgpr_private_segment_size 0
		.amdhsa_uses_dynamic_stack 0
		.amdhsa_enable_private_segment 0
		.amdhsa_system_sgpr_workgroup_id_x 1
		.amdhsa_system_sgpr_workgroup_id_y 0
		.amdhsa_system_sgpr_workgroup_id_z 0
		.amdhsa_system_sgpr_workgroup_info 0
		.amdhsa_system_vgpr_workitem_id 2
		.amdhsa_next_free_vgpr 254
		.amdhsa_next_free_sgpr 102
		.amdhsa_accum_offset 256
		.amdhsa_reserve_vcc 1
		.amdhsa_float_round_mode_32 0
		.amdhsa_float_round_mode_16_64 0
		.amdhsa_float_denorm_mode_32 3
		.amdhsa_float_denorm_mode_16_64 3
		.amdhsa_dx10_clamp 1
		.amdhsa_ieee_mode 1
		.amdhsa_fp16_overflow 0
		.amdhsa_tg_split 0
		.amdhsa_exception_fp_ieee_invalid_op 0
		.amdhsa_exception_fp_denorm_src 0
		.amdhsa_exception_fp_ieee_div_zero 0
		.amdhsa_exception_fp_ieee_overflow 0
		.amdhsa_exception_fp_ieee_underflow 0
		.amdhsa_exception_fp_ieee_inexact 0
		.amdhsa_exception_int_div_zero 0
	.end_amdhsa_kernel

amdhsa.kernels:
  - .agpr_count:     0
    .args:
      - .offset:         0
        .size:           144
        .value_kind:     by_value
      - .offset:         144
        .size:           4
        .value_kind:     hidden_block_count_x
      - .offset:         148
        .size:           4
        .value_kind:     hidden_block_count_y
      - .offset:         152
        .size:           4
        .value_kind:     hidden_block_count_z
      - .offset:         156
        .size:           2
        .value_kind:     hidden_group_size_x
      - .offset:         158
        .size:           2
        .value_kind:     hidden_group_size_y
      - .offset:         160
        .size:           2
        .value_kind:     hidden_group_size_z
      - .offset:         162
        .size:           2
        .value_kind:     hidden_remainder_x
      - .offset:         164
        .size:           2
        .value_kind:     hidden_remainder_y
      - .offset:         166
        .size:           2
        .value_kind:     hidden_remainder_z
      - .offset:         184
        .size:           8
        .value_kind:     hidden_global_offset_x
      - .offset:         192
        .size:           8
        .value_kind:     hidden_global_offset_y
      - .offset:         200
        .size:           8
        .value_kind:     hidden_global_offset_z
      - .offset:         208
        .size:           2
        .value_kind:     hidden_grid_dims
      - .offset:         232
        .size:           8
        .value_kind:     hidden_multigrid_sync_arg
      - .offset:         264
        .size:           4
        .value_kind:     hidden_dynamic_lds_size
    .group_segment_fixed_size: 0
    .kernarg_segment_align: 8
    .kernarg_segment_size: 400
    .language:       OpenCL C
    .language_version:
      - 2
      - 0
    .max_flat_workgroup_size: 512
    .name:           _Z8mega_fwd4Args
    .private_segment_fixed_size: 0
    .sgpr_count:     108
    .sgpr_spill_count: 116
    .symbol:         _Z8mega_fwd4Args.kd
    .uniform_work_group_size: 1
    .uses_dynamic_stack: false
    .vgpr_count:     254
    .vgpr_spill_count: 0
    .wavefront_size: 64
